# FFN-F2 epilogue: conv FMA chains start from the bias (one packed add fewer per element pair); FFN-F2 loop head kept at 40 mod 64
# baseline (speedup 1.0000x reference)
.LBB0_1060:
	s_lshl_b32 s0, s3, 8
	s_add_i32 s0, s0, s60
	s_cmpk_lt_i32 s0, 0x2000
	s_movk_i32 s20, 0xfff
	v_lshl_or_b32 v192, s2, 8, v223
	s_cselect_b32 s14, s20, 0x7ff
	s_or_b32 s2, s0, 63
	s_and_b32 s1, s14, s0
	s_and_b32 s15, s14, s2
	v_or_b32_e32 v226, s0, v221
	v_mov_b64_e32 v[208:209], s[10:11]
	s_movk_i32 s26, 0x2c00
	v_ashrrev_i32_e32 v193, 31, v192
	v_mad_i64_i32 v[152:153], s[2:3], v226, s26, v[208:209]
	s_cmp_eq_u32 s1, 0
	s_mul_i32 s1, s0, 0x2c00
	v_lshlrev_b64 v[204:205], 1, v[192:193]
	s_cselect_b64 s[62:63], -1, 0
	s_mul_hi_i32 s3, s0, 0x2c00
	s_add_u32 s2, s10, s1
	v_lshl_add_u64 v[194:195], v[152:153], 0, v[204:205]
	s_mov_b32 s21, 0x2c000
	s_addc_u32 s3, s11, s3
	v_add_co_u32_e32 v198, vcc, s21, v194
	s_and_b64 s[12:13], s[62:63], exec
	s_nop 0
	v_addc_co_u32_e32 v199, vcc, 0, v195, vcc
	s_mov_b32 s22, 0x58000
	s_cselect_b32 s12, 0, 0xffffd400
	s_cselect_b32 s13, 0, -1
	s_cmp_eq_u32 s15, s14
	v_add_co_u32_e32 v200, vcc, s22, v194
	s_cselect_b64 s[50:51], -1, 0
	v_lshlrev_b64 v[88:89], 2, v[192:193]
	v_addc_co_u32_e32 v201, vcc, 0, v195, vcc
	s_mov_b32 s23, 0x84000
	v_lshl_add_u64 v[202:203], s[2:3], 0, v[204:205]
	s_and_b64 s[2:3], s[50:51], exec
	v_lshl_add_u64 v[190:191], s[18:19], 0, v[88:89]
	v_lshl_add_u64 v[90:91], s[46:47], 0, v[88:89]
	v_lshl_add_u64 v[96:97], s[48:49], 0, v[88:89]
	v_add_co_u32_e32 v206, vcc, s23, v194
	s_cselect_b32 s72, 0, 0xb0000
	v_lshl_add_u64 v[188:189], s[30:31], 0, v[88:89]
	global_load_dwordx4 v[100:103], v[190:191], off offset:16
	global_load_dwordx4 v[120:123], v[190:191], off
	global_load_dwordx4 v[92:95], v[90:91], off offset:16
	global_load_dwordx4 v[112:115], v[90:91], off
	s_nop 0
	global_load_dwordx4 v[88:91], v[96:97], off offset:16
	global_load_dwordx4 v[108:111], v[96:97], off
	s_nop 0
	global_load_dwordx4 v[96:99], v[188:189], off offset:16
	global_load_dwordx4 v[116:119], v[188:189], off
	global_load_dwordx4 v[172:175], v[194:195], off
	v_addc_co_u32_e32 v207, vcc, 0, v195, vcc
	v_lshl_add_u64 v[196:197], v[202:203], 0, s[12:13]
	v_lshl_add_u64 v[202:203], v[202:203], 0, s[72:73]
	global_load_dwordx4 v[168:171], v[198:199], off
	global_load_dwordx4 v[164:167], v[200:201], off
	global_load_dwordx4 v[152:155], v[206:207], off
	global_load_dwordx4 v[232:235], v[202:203], off
	global_load_dwordx4 v[228:231], v[196:197], off
	v_or_b32_e32 v193, v211, v219
	v_lshlrev_b32_e32 v193, 2, v193
	v_or_b32_e32 v225, v219, v212
	v_lshlrev_b32_e32 v225, 2, v225
	s_add_i32 s12, s0, 0x80
	s_cmpk_lt_i32 s12, 0x2000
	s_cselect_b32 s13, s20, 0x7ff
	s_addk_i32 s0, 0xbf
	s_and_b32 s14, s13, s12
	s_and_b32 s15, s13, s0
	s_cmp_eq_u32 s14, 0
	s_waitcnt vmcnt(0)
	ds_bpermute_b32 v239, v193, v172
	ds_bpermute_b32 v240, v193, v173
	ds_bpermute_b32 v241, v193, v174
	ds_bpermute_b32 v242, v193, v175
	ds_bpermute_b32 v243, v225, v168
	ds_bpermute_b32 v244, v225, v169
	ds_bpermute_b32 v245, v225, v170
	v_cndmask_b32_e64 v227, v235, 0, s[50:51]
	v_cndmask_b32_e64 v236, v230, 0, s[62:63]
	v_cndmask_b32_e64 v237, v229, 0, s[62:63]
	v_cndmask_b32_e64 v229, v233, 0, s[50:51]
	v_cndmask_b32_e64 v230, v232, 0, s[50:51]
	ds_bpermute_b32 v232, v225, v172
	ds_bpermute_b32 v233, v225, v173
	v_cndmask_b32_e64 v238, v228, 0, s[62:63]
	v_cndmask_b32_e64 v228, v234, 0, s[50:51]
	ds_bpermute_b32 v234, v225, v174
	ds_bpermute_b32 v235, v225, v175
	ds_bpermute_b32 v246, v225, v171
	s_waitcnt lgkmcnt(11)
	v_cndmask_b32_e64 v238, v239, v238, s[4:5]
	s_waitcnt lgkmcnt(4)
	v_cndmask_b32_e64 v247, v232, v243, s[6:7]
	s_waitcnt lgkmcnt(3)
	v_cndmask_b32_e64 v249, v233, v244, s[6:7]
	v_lshlrev_b32_e32 v232, 16, v238
	v_and_b32_e32 v233, 0xffff0000, v238
	v_cndmask_b32_e64 v248, v240, v237, s[4:5]
	v_cndmask_b32_e64 v250, v241, v236, s[4:5]
	v_pk_fma_f32 v[232:233], v[120:121], v[232:233], v[116:117]
	v_lshlrev_b32_e32 v236, 16, v172
	v_and_b32_e32 v237, 0xffff0000, v172
	s_waitcnt lgkmcnt(2)
	v_cndmask_b32_e64 v251, v234, v245, s[6:7]
	s_waitcnt lgkmcnt(0)
	v_cndmask_b32_e64 v252, v235, v246, s[6:7]
	v_lshlrev_b32_e32 v234, 16, v247
	v_and_b32_e32 v235, 0xffff0000, v247
	v_pk_fma_f32 v[232:233], v[112:113], v[236:237], v[232:233]
	v_cndmask_b32_e64 v231, v231, 0, s[62:63]
	v_pk_fma_f32 v[232:233], v[108:109], v[234:235], v[232:233]
	v_cndmask_b32_e64 v231, v242, v231, s[4:5]
	ds_bpermute_b32 v236, v225, v166
	v_mul_f32_e32 v172, 0xbfb8aa3b, v232
	v_exp_f32_e32 v172, v172
	ds_bpermute_b32 v237, v225, v167
	v_add_f32_e32 v172, 1.0, v172
	v_rcp_f32_e32 v234, v172
	v_mul_f32_e32 v172, 0xbfb8aa3b, v233
	v_exp_f32_e32 v172, v172
	s_nop 0
	v_add_f32_e32 v172, 1.0, v172
	v_rcp_f32_e32 v235, v172
	v_lshlrev_b32_e32 v172, 16, v173
	v_and_b32_e32 v173, 0xffff0000, v173
	v_pk_mul_f32 v[232:233], v[232:233], v[234:235]
	s_nop 0
	v_pk_mul_f32 v[160:161], v[160:161], v[232:233]
	v_lshlrev_b32_e32 v232, 16, v248
	v_and_b32_e32 v233, 0xffff0000, v248
	v_pk_mul_f32 v[232:233], v[122:123], v[232:233]
	v_lshlrev_b32_e32 v234, 16, v249
	v_and_b32_e32 v235, 0xffff0000, v249
	v_pk_fma_f32 v[172:173], v[114:115], v[172:173], v[232:233]
	s_nop 0
	v_pk_fma_f32 v[172:173], v[110:111], v[234:235], v[172:173]
	v_lshlrev_b32_e32 v234, 16, v174
	v_pk_add_f32 v[172:173], v[118:119], v[172:173]
	v_and_b32_e32 v235, 0xffff0000, v174
	v_mul_f32_e32 v232, 0xbfb8aa3b, v172
	v_mul_f32_e32 v233, 0xbfb8aa3b, v173
	v_exp_f32_e32 v232, v232
	v_exp_f32_e32 v233, v233
	v_add_f32_e32 v232, 1.0, v232
	v_add_f32_e32 v233, 1.0, v233
	v_rcp_f32_e32 v232, v232
	v_rcp_f32_e32 v233, v233
	s_nop 0
	v_pk_mul_f32 v[172:173], v[172:173], v[232:233]
	s_nop 0
	v_pk_mul_f32 v[162:163], v[162:163], v[172:173]
	v_lshlrev_b32_e32 v172, 16, v250
	v_and_b32_e32 v173, 0xffff0000, v250
	v_pk_fma_f32 v[172:173], v[100:101], v[172:173], v[96:97]
	v_lshlrev_b32_e32 v232, 16, v251
	v_and_b32_e32 v233, 0xffff0000, v251
	v_pk_fma_f32 v[172:173], v[92:93], v[234:235], v[172:173]
	ds_bpermute_b32 v234, v225, v164
	v_pk_fma_f32 v[172:173], v[88:89], v[232:233], v[172:173]
	ds_bpermute_b32 v235, v225, v165
	s_nop 0
	v_mul_f32_e32 v174, 0xbfb8aa3b, v172
	v_exp_f32_e32 v174, v174
	s_nop 0
	v_add_f32_e32 v174, 1.0, v174
	v_rcp_f32_e32 v232, v174
	v_mul_f32_e32 v174, 0xbfb8aa3b, v173
	v_exp_f32_e32 v174, v174
	s_nop 0
	v_add_f32_e32 v174, 1.0, v174
	v_rcp_f32_e32 v233, v174
	v_lshlrev_b32_e32 v174, 16, v175
	v_and_b32_e32 v175, 0xffff0000, v175
	v_pk_mul_f32 v[172:173], v[172:173], v[232:233]
	s_nop 0
	v_pk_mul_f32 v[156:157], v[156:157], v[172:173]
	v_lshlrev_b32_e32 v172, 16, v231
	v_and_b32_e32 v173, 0xffff0000, v231
	v_pk_fma_f32 v[172:173], v[102:103], v[172:173], v[98:99]
	v_lshlrev_b32_e32 v232, 16, v252
	v_and_b32_e32 v233, 0xffff0000, v252
	v_pk_fma_f32 v[172:173], v[94:95], v[174:175], v[172:173]
	ds_bpermute_b32 v231, v193, v170
	v_pk_fma_f32 v[172:173], v[90:91], v[232:233], v[172:173]
	ds_bpermute_b32 v232, v193, v171
	v_or_b32_e32 v233, 16, v226
	v_mul_f32_e32 v174, 0xbfb8aa3b, v172
	v_mul_f32_e32 v175, 0xbfb8aa3b, v173
	v_exp_f32_e32 v174, v174
	v_exp_f32_e32 v175, v175
	s_waitcnt lgkmcnt(0)
	v_cndmask_b32_e64 v242, v232, v242, s[4:5]
	v_add_f32_e32 v174, 1.0, v174
	v_add_f32_e32 v175, 1.0, v175
	v_rcp_f32_e32 v174, v174
	v_rcp_f32_e32 v175, v175
	s_nop 0
	v_pk_mul_f32 v[172:173], v[172:173], v[174:175]
	ds_bpermute_b32 v174, v193, v168
	v_pk_mul_f32 v[172:173], v[158:159], v[172:173]
	v_cvt_pk_bf16_f32 v158, v160, v161
	v_cvt_pk_bf16_f32 v161, v172, v173
	v_mov_b64_e32 v[172:173], s[16:17]
	v_cvt_pk_bf16_f32 v160, v156, v157
	v_mad_i64_i32 v[156:157], s[2:3], v226, s26, v[172:173]
	v_cvt_pk_bf16_f32 v159, v162, v163
	v_lshl_add_u64 v[156:157], v[156:157], 0, v[204:205]
	global_store_dwordx4 v[156:157], v[158:161], off
	v_lshlrev_b32_e32 v162, 16, v168
	v_and_b32_e32 v163, 0xffff0000, v168
	s_waitcnt lgkmcnt(0)
	v_cndmask_b32_e64 v159, v174, v239, s[4:5]
	v_lshlrev_b32_e32 v158, 16, v159
	v_and_b32_e32 v159, 0xffff0000, v159
	v_cndmask_b32_e64 v161, v243, v234, s[6:7]
	v_pk_fma_f32 v[158:159], v[120:121], v[158:159], v[116:117]
	v_lshlrev_b32_e32 v160, 16, v161
	v_and_b32_e32 v161, 0xffff0000, v161
	v_pk_fma_f32 v[158:159], v[112:113], v[162:163], v[158:159]
	ds_bpermute_b32 v175, v193, v169
	v_pk_fma_f32 v[158:159], v[108:109], v[160:161], v[158:159]
	v_cndmask_b32_e64 v239, v244, v235, s[6:7]
	v_lshlrev_b32_e32 v162, 16, v169
	v_mul_f32_e32 v160, 0xbfb8aa3b, v158
	v_mul_f32_e32 v161, 0xbfb8aa3b, v159
	v_exp_f32_e32 v160, v160
	v_exp_f32_e32 v161, v161
	s_waitcnt lgkmcnt(0)
	v_cndmask_b32_e64 v238, v175, v240, s[4:5]
	v_and_b32_e32 v163, 0xffff0000, v169
	v_add_f32_e32 v160, 1.0, v160
	v_add_f32_e32 v161, 1.0, v161
	v_rcp_f32_e32 v160, v160
	v_rcp_f32_e32 v161, v161
	v_cndmask_b32_e64 v240, v231, v241, s[4:5]
	v_cndmask_b32_e64 v241, v245, v236, s[6:7]
	v_cndmask_b32_e64 v243, v246, v237, s[6:7]
	v_pk_mul_f32 v[158:159], v[158:159], v[160:161]
	v_lshlrev_b32_e32 v160, 16, v239
	v_pk_mul_f32 v[148:149], v[148:149], v[158:159]
	v_lshlrev_b32_e32 v158, 16, v238
	v_and_b32_e32 v159, 0xffff0000, v238
	v_pk_fma_f32 v[158:159], v[122:123], v[158:159], v[118:119]
	v_and_b32_e32 v161, 0xffff0000, v239
	v_pk_fma_f32 v[158:159], v[114:115], v[162:163], v[158:159]
	v_lshlrev_b32_e32 v162, 16, v170
	v_pk_fma_f32 v[158:159], v[110:111], v[160:161], v[158:159]
	v_and_b32_e32 v163, 0xffff0000, v170
	v_cvt_pk_bf16_f32 v148, v148, v149
	v_mul_f32_e32 v160, 0xbfb8aa3b, v158
	v_mul_f32_e32 v161, 0xbfb8aa3b, v159
	v_exp_f32_e32 v160, v160
	v_exp_f32_e32 v161, v161
	ds_bpermute_b32 v168, v225, v153
	ds_bpermute_b32 v169, v225, v154
	v_add_f32_e32 v160, 1.0, v160
	v_add_f32_e32 v161, 1.0, v161
	v_rcp_f32_e32 v160, v160
	v_rcp_f32_e32 v161, v161
	ds_bpermute_b32 v170, v225, v155
	v_pk_mul_f32 v[158:159], v[158:159], v[160:161]
	s_nop 0
	v_pk_mul_f32 v[150:151], v[150:151], v[158:159]
	v_lshlrev_b32_e32 v158, 16, v240
	v_and_b32_e32 v159, 0xffff0000, v240
	v_pk_fma_f32 v[158:159], v[100:101], v[158:159], v[96:97]
	v_lshlrev_b32_e32 v160, 16, v241
	v_and_b32_e32 v161, 0xffff0000, v241
	v_pk_fma_f32 v[158:159], v[92:93], v[162:163], v[158:159]
	v_lshlrev_b32_e32 v162, 16, v171
	v_pk_fma_f32 v[158:159], v[88:89], v[160:161], v[158:159]
	v_and_b32_e32 v163, 0xffff0000, v171
	v_cvt_pk_bf16_f32 v149, v150, v151
	v_mul_f32_e32 v160, 0xbfb8aa3b, v158
	v_mul_f32_e32 v161, 0xbfb8aa3b, v159
	v_exp_f32_e32 v160, v160
	v_exp_f32_e32 v161, v161
	v_add_f32_e32 v160, 1.0, v160
	v_add_f32_e32 v161, 1.0, v161
	v_rcp_f32_e32 v160, v160
	v_rcp_f32_e32 v161, v161
	s_nop 0
	v_pk_mul_f32 v[158:159], v[158:159], v[160:161]
	s_nop 0
	v_pk_mul_f32 v[144:145], v[144:145], v[158:159]
	v_lshlrev_b32_e32 v158, 16, v242
	v_and_b32_e32 v159, 0xffff0000, v242
	v_pk_fma_f32 v[158:159], v[102:103], v[158:159], v[98:99]
	v_lshlrev_b32_e32 v160, 16, v243
	v_and_b32_e32 v161, 0xffff0000, v243
	v_pk_fma_f32 v[158:159], v[94:95], v[162:163], v[158:159]
	ds_bpermute_b32 v163, v225, v152
	v_pk_fma_f32 v[158:159], v[90:91], v[160:161], v[158:159]
	v_cvt_pk_bf16_f32 v150, v144, v145
	v_mad_i64_i32 v[144:145], s[2:3], v233, s26, v[172:173]
	v_mul_f32_e32 v160, 0xbfb8aa3b, v158
	v_mul_f32_e32 v161, 0xbfb8aa3b, v159
	v_exp_f32_e32 v160, v160
	v_exp_f32_e32 v161, v161
	s_waitcnt lgkmcnt(1)
	v_cndmask_b32_e64 v233, v237, v170, s[6:7]
	v_or_b32_e32 v162, 32, v226
	v_add_f32_e32 v160, 1.0, v160
	v_add_f32_e32 v161, 1.0, v161
	v_rcp_f32_e32 v160, v160
	v_rcp_f32_e32 v161, v161
	s_nop 0
	v_pk_mul_f32 v[158:159], v[158:159], v[160:161]
	s_nop 0
	v_pk_mul_f32 v[146:147], v[146:147], v[158:159]
	ds_bpermute_b32 v158, v193, v164
	v_cvt_pk_bf16_f32 v151, v146, v147
	v_lshl_add_u64 v[146:147], v[144:145], 0, v[204:205]
	global_store_dwordx4 v[146:147], v[148:151], off
	ds_bpermute_b32 v159, v193, v165
	s_waitcnt lgkmcnt(1)
	v_cndmask_b32_e64 v145, v158, v174, s[4:5]
	v_lshlrev_b32_e32 v144, 16, v145
	v_and_b32_e32 v145, 0xffff0000, v145
	v_cndmask_b32_e64 v149, v234, v163, s[6:7]
	v_pk_fma_f32 v[144:145], v[120:121], v[144:145], v[116:117]
	v_lshlrev_b32_e32 v150, 16, v164
	v_and_b32_e32 v151, 0xffff0000, v164
	v_lshlrev_b32_e32 v148, 16, v149
	v_and_b32_e32 v149, 0xffff0000, v149
	v_pk_fma_f32 v[144:145], v[112:113], v[150:151], v[144:145]
	s_waitcnt lgkmcnt(0)
	v_cndmask_b32_e64 v171, v159, v175, s[4:5]
	v_pk_fma_f32 v[144:145], v[108:109], v[148:149], v[144:145]
	v_cndmask_b32_e64 v174, v235, v168, s[6:7]
	v_lshlrev_b32_e32 v150, 16, v165
	v_mul_f32_e32 v148, 0xbfb8aa3b, v144
	v_mul_f32_e32 v149, 0xbfb8aa3b, v145
	v_exp_f32_e32 v148, v148
	v_exp_f32_e32 v149, v149
	v_and_b32_e32 v151, 0xffff0000, v165
	ds_bpermute_b32 v160, v193, v166
	v_add_f32_e32 v148, 1.0, v148
	v_add_f32_e32 v149, 1.0, v149
	v_rcp_f32_e32 v148, v148
	v_rcp_f32_e32 v149, v149
	s_waitcnt lgkmcnt(0)
	v_cndmask_b32_e64 v175, v160, v231, s[4:5]
	v_cndmask_b32_e64 v231, v236, v169, s[6:7]
	ds_bpermute_b32 v161, v193, v167
	v_pk_mul_f32 v[144:145], v[144:145], v[148:149]
	v_lshlrev_b32_e32 v148, 16, v174
	v_pk_mul_f32 v[140:141], v[140:141], v[144:145]
	v_lshlrev_b32_e32 v144, 16, v171
	v_and_b32_e32 v145, 0xffff0000, v171
	v_pk_fma_f32 v[144:145], v[122:123], v[144:145], v[118:119]
	v_and_b32_e32 v149, 0xffff0000, v174
	v_pk_fma_f32 v[144:145], v[114:115], v[150:151], v[144:145]
	v_lshlrev_b32_e32 v150, 16, v166
	v_pk_fma_f32 v[144:145], v[110:111], v[148:149], v[144:145]
	v_and_b32_e32 v151, 0xffff0000, v166
	s_waitcnt lgkmcnt(0)
	v_cndmask_b32_e64 v232, v161, v232, s[4:5]
	v_mul_f32_e32 v148, 0xbfb8aa3b, v144
	v_mul_f32_e32 v149, 0xbfb8aa3b, v145
	v_exp_f32_e32 v148, v148
	v_exp_f32_e32 v149, v149
	v_or_b32_e32 v164, s12, v221
	v_add_f32_e32 v148, 1.0, v148
	v_add_f32_e32 v149, 1.0, v149
	v_rcp_f32_e32 v148, v148
	v_rcp_f32_e32 v149, v149
	s_nop 0
	v_pk_mul_f32 v[144:145], v[144:145], v[148:149]
	s_nop 0
	v_pk_mul_f32 v[142:143], v[142:143], v[144:145]
	v_lshlrev_b32_e32 v144, 16, v175
	v_and_b32_e32 v145, 0xffff0000, v175
	v_pk_fma_f32 v[144:145], v[100:101], v[144:145], v[96:97]
	v_lshlrev_b32_e32 v148, 16, v231
	v_and_b32_e32 v149, 0xffff0000, v231
	v_pk_fma_f32 v[144:145], v[92:93], v[150:151], v[144:145]
	v_lshlrev_b32_e32 v150, 16, v167
	v_pk_fma_f32 v[144:145], v[88:89], v[148:149], v[144:145]
	v_and_b32_e32 v151, 0xffff0000, v167
	s_nop 0
	v_mul_f32_e32 v148, 0xbfb8aa3b, v144
	v_mul_f32_e32 v149, 0xbfb8aa3b, v145
	v_exp_f32_e32 v148, v148
	v_exp_f32_e32 v149, v149
	v_add_f32_e32 v148, 1.0, v148
	v_add_f32_e32 v149, 1.0, v149
	v_rcp_f32_e32 v148, v148
	v_rcp_f32_e32 v149, v149
	s_nop 0
	v_pk_mul_f32 v[144:145], v[144:145], v[148:149]
	s_nop 0
	v_pk_mul_f32 v[144:145], v[136:137], v[144:145]
	v_lshlrev_b32_e32 v136, 16, v232
	v_and_b32_e32 v137, 0xffff0000, v232
	v_pk_fma_f32 v[136:137], v[102:103], v[136:137], v[98:99]
	v_lshlrev_b32_e32 v148, 16, v233
	v_and_b32_e32 v149, 0xffff0000, v233
	v_pk_fma_f32 v[136:137], v[94:95], v[150:151], v[136:137]
	v_cndmask_b32_e64 v150, v169, v228, s[6:7]
	v_pk_fma_f32 v[136:137], v[90:91], v[148:149], v[136:137]
	s_nop 0
	s_nop 0
	v_mul_f32_e32 v148, 0xbfb8aa3b, v136
	v_mul_f32_e32 v149, 0xbfb8aa3b, v137
	v_exp_f32_e32 v148, v148
	v_exp_f32_e32 v149, v149
	v_add_f32_e32 v148, 1.0, v148
	v_add_f32_e32 v149, 1.0, v149
	v_rcp_f32_e32 v148, v148
	v_rcp_f32_e32 v149, v149
	s_nop 0
	v_pk_mul_f32 v[136:137], v[136:137], v[148:149]
	s_nop 0
	v_pk_mul_f32 v[148:149], v[138:139], v[136:137]
	v_cvt_pk_bf16_f32 v136, v140, v141
	v_mad_i64_i32 v[140:141], s[2:3], v162, s26, v[172:173]
	v_cvt_pk_bf16_f32 v137, v142, v143
	v_cvt_pk_bf16_f32 v138, v144, v145
	v_cvt_pk_bf16_f32 v139, v148, v149
	v_lshl_add_u64 v[148:149], v[140:141], 0, v[204:205]
	global_store_dwordx4 v[148:149], v[136:139], off
	ds_bpermute_b32 v136, v193, v152
	ds_bpermute_b32 v137, v193, v153
	ds_bpermute_b32 v138, v193, v154
	ds_bpermute_b32 v139, v193, v155
	v_cndmask_b32_e64 v141, v163, v230, s[6:7]
	s_waitcnt lgkmcnt(3)
	v_cndmask_b32_e64 v140, v136, v158, s[4:5]
	s_waitcnt lgkmcnt(2)
	v_cndmask_b32_e64 v143, v137, v159, s[4:5]
	v_lshlrev_b32_e32 v136, 16, v140
	v_and_b32_e32 v137, 0xffff0000, v140
	s_waitcnt lgkmcnt(1)
	v_cndmask_b32_e64 v145, v138, v160, s[4:5]
	s_waitcnt lgkmcnt(0)
	v_cndmask_b32_e64 v151, v139, v161, s[4:5]
	v_lshlrev_b32_e32 v138, 16, v141
	v_and_b32_e32 v139, 0xffff0000, v141
	v_pk_fma_f32 v[136:137], v[120:121], v[136:137], v[116:117]
	v_lshlrev_b32_e32 v140, 16, v152
	v_and_b32_e32 v141, 0xffff0000, v152
	v_pk_fma_f32 v[136:137], v[112:113], v[140:141], v[136:137]
	v_cndmask_b32_e64 v144, v168, v229, s[6:7]
	v_pk_fma_f32 v[136:137], v[108:109], v[138:139], v[136:137]
	v_lshlrev_b32_e32 v140, 16, v153
	v_and_b32_e32 v141, 0xffff0000, v153
	v_mul_f32_e32 v138, 0xbfb8aa3b, v136
	v_mul_f32_e32 v139, 0xbfb8aa3b, v137
	v_exp_f32_e32 v138, v138
	v_exp_f32_e32 v139, v139
	v_cndmask_b32_e64 v158, v170, v227, s[6:7]
	v_or_b32_e32 v142, 48, v226
	v_add_f32_e32 v138, 1.0, v138
	v_add_f32_e32 v139, 1.0, v139
	v_rcp_f32_e32 v138, v138
	v_rcp_f32_e32 v139, v139
	s_nop 0
	v_pk_mul_f32 v[136:137], v[136:137], v[138:139]
	s_nop 0
	v_pk_mul_f32 v[132:133], v[132:133], v[136:137]
	v_lshlrev_b32_e32 v136, 16, v143
	v_and_b32_e32 v137, 0xffff0000, v143
	v_pk_fma_f32 v[136:137], v[122:123], v[136:137], v[118:119]
	v_lshlrev_b32_e32 v138, 16, v144
	v_and_b32_e32 v139, 0xffff0000, v144
	v_pk_fma_f32 v[136:137], v[114:115], v[140:141], v[136:137]
	v_lshlrev_b32_e32 v140, 16, v154
	v_pk_fma_f32 v[136:137], v[110:111], v[138:139], v[136:137]
	v_and_b32_e32 v141, 0xffff0000, v154
	s_nop 0
	v_mul_f32_e32 v138, 0xbfb8aa3b, v136
	v_mul_f32_e32 v139, 0xbfb8aa3b, v137
	v_exp_f32_e32 v138, v138
	v_exp_f32_e32 v139, v139
	v_add_f32_e32 v138, 1.0, v138
	v_add_f32_e32 v139, 1.0, v139
	v_rcp_f32_e32 v138, v138
	v_rcp_f32_e32 v139, v139
	s_nop 0
	v_pk_mul_f32 v[136:137], v[136:137], v[138:139]
	s_nop 0
	v_pk_mul_f32 v[134:135], v[134:135], v[136:137]
	v_lshlrev_b32_e32 v136, 16, v145
	v_and_b32_e32 v137, 0xffff0000, v145
	v_pk_fma_f32 v[136:137], v[100:101], v[136:137], v[96:97]
	v_lshlrev_b32_e32 v138, 16, v150
	v_and_b32_e32 v139, 0xffff0000, v150
	v_pk_fma_f32 v[136:137], v[92:93], v[140:141], v[136:137]
	v_lshlrev_b32_e32 v140, 16, v155
	v_pk_fma_f32 v[136:137], v[88:89], v[138:139], v[136:137]
	v_and_b32_e32 v141, 0xffff0000, v155
	s_nop 0
	v_mul_f32_e32 v138, 0xbfb8aa3b, v136
	v_mul_f32_e32 v139, 0xbfb8aa3b, v137
	v_exp_f32_e32 v138, v138
	v_exp_f32_e32 v139, v139
	v_add_f32_e32 v138, 1.0, v138
	v_add_f32_e32 v139, 1.0, v139
	v_rcp_f32_e32 v138, v138
	v_rcp_f32_e32 v139, v139
	s_nop 0
	v_pk_mul_f32 v[136:137], v[136:137], v[138:139]
	s_nop 0
	v_pk_mul_f32 v[136:137], v[128:129], v[136:137]
	v_lshlrev_b32_e32 v128, 16, v151
	v_and_b32_e32 v129, 0xffff0000, v151
	v_pk_fma_f32 v[128:129], v[102:103], v[128:129], v[98:99]
	v_lshlrev_b32_e32 v138, 16, v158
	v_and_b32_e32 v139, 0xffff0000, v158
	v_pk_fma_f32 v[128:129], v[94:95], v[140:141], v[128:129]
	s_nop 0
	v_pk_fma_f32 v[128:129], v[90:91], v[138:139], v[128:129]
	s_nop 0
	s_nop 0
	v_mul_f32_e32 v138, 0xbfb8aa3b, v128
	v_mul_f32_e32 v139, 0xbfb8aa3b, v129
	v_exp_f32_e32 v138, v138
	v_exp_f32_e32 v139, v139
	v_add_f32_e32 v138, 1.0, v138
	v_add_f32_e32 v139, 1.0, v139
	v_rcp_f32_e32 v138, v138
	v_rcp_f32_e32 v139, v139
	s_nop 0
	v_pk_mul_f32 v[128:129], v[128:129], v[138:139]
	s_nop 0
	v_pk_mul_f32 v[138:139], v[130:131], v[128:129]
	v_cvt_pk_bf16_f32 v128, v132, v133
	v_mad_i64_i32 v[132:133], s[2:3], v142, s26, v[172:173]
	v_cvt_pk_bf16_f32 v129, v134, v135
	v_cvt_pk_bf16_f32 v130, v136, v137
	v_cvt_pk_bf16_f32 v131, v138, v139
	v_lshl_add_u64 v[144:145], v[132:133], 0, v[204:205]
	global_store_dwordx4 v[144:145], v[128:131], off
	s_nop 1
	v_mad_i64_i32 v[128:129], s[2:3], v164, s26, v[208:209]
	v_lshl_add_u64 v[150:151], v[128:129], 0, v[204:205]
	v_add_co_u32_e32 v152, vcc, s21, v150
	s_mul_hi_i32 s2, s12, 0x2c00
	s_nop 0
	v_addc_co_u32_e32 v153, vcc, 0, v151, vcc
	v_add_co_u32_e32 v154, vcc, s22, v150
	global_load_dwordx4 v[140:143], v[150:151], off
	global_load_dwordx4 v[136:139], v[152:153], off
	v_addc_co_u32_e32 v155, vcc, 0, v151, vcc
	v_add_co_u32_e32 v158, vcc, s23, v150
	s_cselect_b64 s[22:23], -1, 0
	s_add_i32 s1, s1, 0x160000
	s_add_u32 s0, s10, s1
	s_addc_u32 s1, s11, s2
	s_and_b64 s[2:3], s[22:23], exec
	v_addc_co_u32_e32 v159, vcc, 0, v151, vcc
	s_cselect_b32 s2, 0, 0xffffd400
	s_cselect_b32 s3, 0, -1
	s_cmp_eq_u32 s15, s13
	s_cselect_b64 vcc, -1, 0
	v_lshl_add_u64 v[160:161], s[0:1], 0, v[204:205]
	s_and_b64 s[0:1], vcc, exec
	s_cselect_b32 s72, 0, 0xb0000
	v_lshl_add_u64 v[162:163], v[160:161], 0, s[2:3]
	v_lshl_add_u64 v[160:161], v[160:161], 0, s[72:73]
	global_load_dwordx4 v[166:169], v[162:163], off
	global_load_dwordx4 v[226:229], v[160:161], off
	global_load_dwordx4 v[132:135], v[154:155], off
	global_load_dwordx4 v[128:131], v[158:159], off
	s_waitcnt vmcnt(5)
	ds_bpermute_b32 v175, v225, v140
	ds_bpermute_b32 v208, v225, v141
	ds_bpermute_b32 v209, v225, v142
	s_waitcnt vmcnt(4)
	ds_bpermute_b32 v231, v225, v136
	ds_bpermute_b32 v232, v225, v137
	ds_bpermute_b32 v233, v225, v138
	ds_bpermute_b32 v230, v225, v143
	ds_bpermute_b32 v234, v225, v139
	s_waitcnt lgkmcnt(4)
	v_cndmask_b32_e64 v175, v175, v231, s[6:7]
	s_waitcnt lgkmcnt(3)
	v_cndmask_b32_e64 v237, v208, v232, s[6:7]
	s_waitcnt lgkmcnt(2)
	v_cndmask_b32_e64 v239, v209, v233, s[6:7]
	v_lshlrev_b32_e32 v208, 16, v140
	v_and_b32_e32 v209, 0xffff0000, v140
	s_waitcnt lgkmcnt(0)
	v_cndmask_b32_e64 v230, v230, v234, s[6:7]
	s_waitcnt vmcnt(3)
	v_cndmask_b32_e64 v170, v168, 0, s[22:23]
	s_waitcnt vmcnt(2)
	v_cndmask_b32_e64 v168, v226, 0, vcc
	ds_bpermute_b32 v226, v193, v140
	v_cndmask_b32_e64 v171, v167, 0, s[22:23]
	v_cndmask_b32_e64 v174, v166, 0, s[22:23]
	v_cndmask_b32_e64 v166, v228, 0, vcc
	v_cndmask_b32_e64 v167, v227, 0, vcc
	ds_bpermute_b32 v227, v193, v141
	ds_bpermute_b32 v228, v193, v142
	s_waitcnt lgkmcnt(2)
	v_cndmask_b32_e64 v235, v226, v174, s[4:5]
	v_lshlrev_b32_e32 v174, 16, v175
	v_and_b32_e32 v175, 0xffff0000, v175
	s_waitcnt lgkmcnt(1)
	v_cndmask_b32_e64 v236, v227, v171, s[4:5]
	s_waitcnt lgkmcnt(0)
	v_cndmask_b32_e64 v238, v228, v170, s[4:5]
	v_lshlrev_b32_e32 v170, 16, v235
	v_and_b32_e32 v171, 0xffff0000, v235
	v_pk_fma_f32 v[170:171], v[120:121], v[170:171], v[116:117]
	v_cndmask_b32_e64 v165, v229, 0, vcc
	v_pk_fma_f32 v[170:171], v[112:113], v[208:209], v[170:171]
	ds_bpermute_b32 v229, v193, v143
	v_pk_fma_f32 v[170:171], v[108:109], v[174:175], v[170:171]
	v_cndmask_b32_e64 v169, v169, 0, s[22:23]
	s_waitcnt lgkmcnt(0)
	v_cndmask_b32_e64 v169, v229, v169, s[4:5]
	v_mul_f32_e32 v140, 0xbfb8aa3b, v170
	v_exp_f32_e32 v140, v140
	s_nop 0
	v_add_f32_e32 v140, 1.0, v140
	v_rcp_f32_e32 v174, v140
	v_mul_f32_e32 v140, 0xbfb8aa3b, v171
	v_exp_f32_e32 v140, v140
	s_nop 0
	v_add_f32_e32 v140, 1.0, v140
	v_rcp_f32_e32 v175, v140
	v_lshlrev_b32_e32 v140, 16, v141
	v_and_b32_e32 v141, 0xffff0000, v141
	v_pk_mul_f32 v[170:171], v[170:171], v[174:175]
	s_nop 0
	v_pk_mul_f32 v[124:125], v[124:125], v[170:171]
	v_lshlrev_b32_e32 v170, 16, v236
	v_and_b32_e32 v171, 0xffff0000, v236
	v_pk_mul_f32 v[170:171], v[122:123], v[170:171]
	v_lshlrev_b32_e32 v174, 16, v237
	v_and_b32_e32 v175, 0xffff0000, v237
	v_pk_fma_f32 v[140:141], v[114:115], v[140:141], v[170:171]
	s_nop 0
	v_pk_fma_f32 v[140:141], v[110:111], v[174:175], v[140:141]
	v_lshlrev_b32_e32 v174, 16, v142
	v_pk_add_f32 v[140:141], v[118:119], v[140:141]
	v_and_b32_e32 v175, 0xffff0000, v142
	v_mul_f32_e32 v170, 0xbfb8aa3b, v140
	v_mul_f32_e32 v171, 0xbfb8aa3b, v141
	v_exp_f32_e32 v170, v170
	v_exp_f32_e32 v171, v171
	v_add_f32_e32 v170, 1.0, v170
	v_add_f32_e32 v171, 1.0, v171
	v_rcp_f32_e32 v170, v170
	v_rcp_f32_e32 v171, v171
	s_nop 0
	v_pk_mul_f32 v[140:141], v[140:141], v[170:171]
	s_nop 0
	v_pk_mul_f32 v[126:127], v[126:127], v[140:141]
	v_lshlrev_b32_e32 v140, 16, v238
	v_and_b32_e32 v141, 0xffff0000, v238
	v_pk_fma_f32 v[140:141], v[100:101], v[140:141], v[96:97]
	v_lshlrev_b32_e32 v170, 16, v239
	v_and_b32_e32 v171, 0xffff0000, v239
	v_pk_fma_f32 v[140:141], v[92:93], v[174:175], v[140:141]
	s_waitcnt vmcnt(1)
	ds_bpermute_b32 v174, v225, v134
	v_pk_fma_f32 v[140:141], v[88:89], v[170:171], v[140:141]
	ds_bpermute_b32 v175, v225, v135
	s_nop 0
	v_mul_f32_e32 v142, 0xbfb8aa3b, v140
	v_exp_f32_e32 v142, v142
	s_nop 0
	v_add_f32_e32 v142, 1.0, v142
	v_rcp_f32_e32 v170, v142
	v_mul_f32_e32 v142, 0xbfb8aa3b, v141
	v_exp_f32_e32 v142, v142
	s_nop 0
	v_add_f32_e32 v142, 1.0, v142
	v_rcp_f32_e32 v171, v142
	v_lshlrev_b32_e32 v142, 16, v143
	v_and_b32_e32 v143, 0xffff0000, v143
	v_pk_mul_f32 v[140:141], v[140:141], v[170:171]
	s_nop 0
	v_pk_mul_f32 v[140:141], v[104:105], v[140:141]
	v_lshlrev_b32_e32 v104, 16, v169
	v_and_b32_e32 v105, 0xffff0000, v169
	v_pk_fma_f32 v[104:105], v[102:103], v[104:105], v[98:99]
	v_lshlrev_b32_e32 v170, 16, v230
	v_and_b32_e32 v171, 0xffff0000, v230
	v_pk_fma_f32 v[104:105], v[94:95], v[142:143], v[104:105]
	v_or_b32_e32 v169, 16, v164
	v_pk_fma_f32 v[104:105], v[90:91], v[170:171], v[104:105]
	ds_bpermute_b32 v170, v225, v132
	ds_bpermute_b32 v171, v225, v133
	v_mul_f32_e32 v142, 0xbfb8aa3b, v104
	v_mul_f32_e32 v143, 0xbfb8aa3b, v105
	v_exp_f32_e32 v142, v142
	v_exp_f32_e32 v143, v143
	s_waitcnt lgkmcnt(0)
	v_cndmask_b32_e64 v209, v232, v171, s[6:7]
	v_add_f32_e32 v142, 1.0, v142
	v_add_f32_e32 v143, 1.0, v143
	v_rcp_f32_e32 v142, v142
	v_rcp_f32_e32 v143, v143
	s_nop 0
	v_pk_mul_f32 v[104:105], v[104:105], v[142:143]
	s_nop 0
	v_pk_mul_f32 v[142:143], v[106:107], v[104:105]
	v_cvt_pk_bf16_f32 v106, v140, v141
	ds_bpermute_b32 v140, v193, v136
	v_cvt_pk_bf16_f32 v104, v124, v125
	v_mad_i64_i32 v[124:125], s[0:1], v164, s26, v[172:173]
	v_cvt_pk_bf16_f32 v105, v126, v127
	v_cvt_pk_bf16_f32 v107, v142, v143
	v_lshl_add_u64 v[124:125], v[124:125], 0, v[204:205]
	global_store_dwordx4 v[124:125], v[104:107], off
	v_lshlrev_b32_e32 v126, 16, v136
	v_and_b32_e32 v127, 0xffff0000, v136
	s_waitcnt lgkmcnt(0)
	v_cndmask_b32_e64 v105, v140, v226, s[4:5]
	v_lshlrev_b32_e32 v104, 16, v105
	v_and_b32_e32 v105, 0xffff0000, v105
	v_cndmask_b32_e64 v107, v231, v170, s[6:7]
	v_pk_fma_f32 v[104:105], v[120:121], v[104:105], v[116:117]
	v_lshlrev_b32_e32 v106, 16, v107
	v_and_b32_e32 v107, 0xffff0000, v107
	v_pk_fma_f32 v[104:105], v[112:113], v[126:127], v[104:105]
	ds_bpermute_b32 v141, v193, v137
	v_pk_fma_f32 v[104:105], v[108:109], v[106:107], v[104:105]
	v_lshlrev_b32_e32 v126, 16, v137
	v_and_b32_e32 v127, 0xffff0000, v137
	v_mul_f32_e32 v106, 0xbfb8aa3b, v104
	v_mul_f32_e32 v107, 0xbfb8aa3b, v105
	v_exp_f32_e32 v106, v106
	v_exp_f32_e32 v107, v107
	s_waitcnt lgkmcnt(0)
	v_cndmask_b32_e64 v208, v141, v227, s[4:5]
	ds_bpermute_b32 v142, v193, v138
	v_add_f32_e32 v106, 1.0, v106
	v_add_f32_e32 v107, 1.0, v107
	v_rcp_f32_e32 v106, v106
	v_rcp_f32_e32 v107, v107
	s_waitcnt lgkmcnt(0)
	v_cndmask_b32_e64 v226, v142, v228, s[4:5]
	v_cndmask_b32_e64 v227, v233, v174, s[6:7]
	ds_bpermute_b32 v143, v193, v139
	v_pk_mul_f32 v[104:105], v[104:105], v[106:107]
	v_lshlrev_b32_e32 v106, 16, v209
	v_pk_mul_f32 v[84:85], v[84:85], v[104:105]
	v_lshlrev_b32_e32 v104, 16, v208
	v_and_b32_e32 v105, 0xffff0000, v208
	v_pk_fma_f32 v[104:105], v[122:123], v[104:105], v[118:119]
	v_and_b32_e32 v107, 0xffff0000, v209
	v_pk_fma_f32 v[104:105], v[114:115], v[126:127], v[104:105]
	v_lshlrev_b32_e32 v126, 16, v138
	v_pk_fma_f32 v[104:105], v[110:111], v[106:107], v[104:105]
	v_and_b32_e32 v127, 0xffff0000, v138
	s_waitcnt lgkmcnt(0)
	v_cndmask_b32_e64 v228, v143, v229, s[4:5]
	v_mul_f32_e32 v106, 0xbfb8aa3b, v104
	v_mul_f32_e32 v107, 0xbfb8aa3b, v105
	v_exp_f32_e32 v106, v106
	v_exp_f32_e32 v107, v107
	v_cndmask_b32_e64 v229, v234, v175, s[6:7]
	s_waitcnt vmcnt(1)
	ds_bpermute_b32 v136, v225, v129
	v_add_f32_e32 v106, 1.0, v106
	v_add_f32_e32 v107, 1.0, v107
	v_rcp_f32_e32 v106, v106
	v_rcp_f32_e32 v107, v107
	ds_bpermute_b32 v137, v225, v130
	ds_bpermute_b32 v138, v225, v131
	v_pk_mul_f32 v[104:105], v[104:105], v[106:107]
	s_nop 0
	v_pk_mul_f32 v[86:87], v[86:87], v[104:105]
	v_lshlrev_b32_e32 v104, 16, v226
	v_and_b32_e32 v105, 0xffff0000, v226
	v_pk_fma_f32 v[104:105], v[100:101], v[104:105], v[96:97]
	v_lshlrev_b32_e32 v106, 16, v227
	v_and_b32_e32 v107, 0xffff0000, v227
	v_pk_fma_f32 v[104:105], v[92:93], v[126:127], v[104:105]
	v_lshlrev_b32_e32 v126, 16, v139
	v_pk_fma_f32 v[104:105], v[88:89], v[106:107], v[104:105]
	v_and_b32_e32 v127, 0xffff0000, v139
	s_nop 0
	v_mul_f32_e32 v106, 0xbfb8aa3b, v104
	v_mul_f32_e32 v107, 0xbfb8aa3b, v105
	v_exp_f32_e32 v106, v106
	v_exp_f32_e32 v107, v107
	v_add_f32_e32 v106, 1.0, v106
	v_add_f32_e32 v107, 1.0, v107
	v_rcp_f32_e32 v106, v106
	v_rcp_f32_e32 v107, v107
	s_nop 0
	v_pk_mul_f32 v[104:105], v[104:105], v[106:107]
	s_nop 0
	v_pk_mul_f32 v[104:105], v[80:81], v[104:105]
	v_lshlrev_b32_e32 v80, 16, v228
	v_and_b32_e32 v81, 0xffff0000, v228
	v_pk_fma_f32 v[80:81], v[102:103], v[80:81], v[98:99]
	v_lshlrev_b32_e32 v106, 16, v229
	v_and_b32_e32 v107, 0xffff0000, v229
	v_pk_fma_f32 v[80:81], v[94:95], v[126:127], v[80:81]
	s_nop 0
	v_pk_fma_f32 v[80:81], v[90:91], v[106:107], v[80:81]
	s_nop 0
	s_nop 0
	v_mul_f32_e32 v106, 0xbfb8aa3b, v80
	v_mul_f32_e32 v107, 0xbfb8aa3b, v81
	v_exp_f32_e32 v106, v106
	v_exp_f32_e32 v107, v107
	v_add_f32_e32 v106, 1.0, v106
	v_add_f32_e32 v107, 1.0, v107
	v_rcp_f32_e32 v106, v106
	v_rcp_f32_e32 v107, v107
	s_nop 0
	v_pk_mul_f32 v[80:81], v[80:81], v[106:107]
	s_nop 0
	v_pk_mul_f32 v[106:107], v[82:83], v[80:81]
	v_cvt_pk_bf16_f32 v81, v86, v87
	ds_bpermute_b32 v86, v193, v132
	v_cvt_pk_bf16_f32 v83, v106, v107
	ds_bpermute_b32 v107, v225, v128
	v_cvt_pk_bf16_f32 v80, v84, v85
	v_mad_i64_i32 v[84:85], s[0:1], v169, s26, v[172:173]
	v_cvt_pk_bf16_f32 v82, v104, v105
	v_lshl_add_u64 v[126:127], v[84:85], 0, v[204:205]
	global_store_dwordx4 v[126:127], v[80:83], off
	v_lshlrev_b32_e32 v84, 16, v132
	v_and_b32_e32 v85, 0xffff0000, v132
	s_waitcnt lgkmcnt(1)
	v_cndmask_b32_e64 v81, v86, v140, s[4:5]
	v_lshlrev_b32_e32 v80, 16, v81
	v_and_b32_e32 v81, 0xffff0000, v81
	s_waitcnt lgkmcnt(0)
	v_cndmask_b32_e64 v83, v170, v107, s[6:7]
	v_pk_fma_f32 v[80:81], v[120:121], v[80:81], v[116:117]
	v_lshlrev_b32_e32 v82, 16, v83
	v_and_b32_e32 v83, 0xffff0000, v83
	v_pk_fma_f32 v[80:81], v[112:113], v[84:85], v[80:81]
	ds_bpermute_b32 v87, v193, v133
	v_pk_fma_f32 v[80:81], v[108:109], v[82:83], v[80:81]
	v_cndmask_b32_e64 v140, v171, v136, s[6:7]
	v_lshlrev_b32_e32 v84, 16, v133
	v_mul_f32_e32 v82, 0xbfb8aa3b, v80
	v_mul_f32_e32 v83, 0xbfb8aa3b, v81
	v_exp_f32_e32 v82, v82
	v_exp_f32_e32 v83, v83
	s_waitcnt lgkmcnt(0)
	v_cndmask_b32_e64 v139, v87, v141, s[4:5]
	v_and_b32_e32 v85, 0xffff0000, v133
	v_add_f32_e32 v82, 1.0, v82
	v_add_f32_e32 v83, 1.0, v83
	v_rcp_f32_e32 v82, v82
	v_rcp_f32_e32 v83, v83
	ds_bpermute_b32 v104, v193, v134
	ds_bpermute_b32 v105, v193, v135
	v_cndmask_b32_e64 v169, v175, v138, s[6:7]
	v_pk_mul_f32 v[80:81], v[80:81], v[82:83]
	v_lshlrev_b32_e32 v82, 16, v140
	v_pk_mul_f32 v[76:77], v[76:77], v[80:81]
	v_lshlrev_b32_e32 v80, 16, v139
	v_and_b32_e32 v81, 0xffff0000, v139
	v_pk_fma_f32 v[80:81], v[122:123], v[80:81], v[118:119]
	v_and_b32_e32 v83, 0xffff0000, v140
	v_pk_fma_f32 v[80:81], v[114:115], v[84:85], v[80:81]
	s_waitcnt lgkmcnt(1)
	v_cndmask_b32_e64 v141, v104, v142, s[4:5]
	v_pk_fma_f32 v[80:81], v[110:111], v[82:83], v[80:81]
	v_cndmask_b32_e64 v142, v174, v137, s[6:7]
	v_lshlrev_b32_e32 v84, 16, v134
	v_mul_f32_e32 v82, 0xbfb8aa3b, v80
	v_mul_f32_e32 v83, 0xbfb8aa3b, v81
	v_exp_f32_e32 v82, v82
	v_exp_f32_e32 v83, v83
	v_and_b32_e32 v85, 0xffff0000, v134
	s_waitcnt lgkmcnt(0)
	v_cndmask_b32_e64 v143, v105, v143, s[4:5]
	v_add_f32_e32 v82, 1.0, v82
	v_add_f32_e32 v83, 1.0, v83
	v_rcp_f32_e32 v82, v82
	v_rcp_f32_e32 v83, v83
	v_or_b32_e32 v106, 32, v164
	v_pk_mul_f32 v[80:81], v[80:81], v[82:83]
	s_nop 0
	v_pk_mul_f32 v[78:79], v[78:79], v[80:81]
	v_lshlrev_b32_e32 v80, 16, v141
	v_and_b32_e32 v81, 0xffff0000, v141
	v_pk_fma_f32 v[80:81], v[100:101], v[80:81], v[96:97]
	v_lshlrev_b32_e32 v82, 16, v142
	v_and_b32_e32 v83, 0xffff0000, v142
	v_pk_fma_f32 v[80:81], v[92:93], v[84:85], v[80:81]
	v_lshlrev_b32_e32 v84, 16, v135
	v_pk_fma_f32 v[80:81], v[88:89], v[82:83], v[80:81]
	v_and_b32_e32 v85, 0xffff0000, v135
	s_nop 0
	v_mul_f32_e32 v82, 0xbfb8aa3b, v80
	v_mul_f32_e32 v83, 0xbfb8aa3b, v81
	v_exp_f32_e32 v82, v82
	v_exp_f32_e32 v83, v83
	v_add_f32_e32 v82, 1.0, v82
	v_add_f32_e32 v83, 1.0, v83
	v_rcp_f32_e32 v82, v82
	v_rcp_f32_e32 v83, v83
	s_nop 0
	v_pk_mul_f32 v[80:81], v[80:81], v[82:83]
	s_nop 0
	v_pk_mul_f32 v[80:81], v[72:73], v[80:81]
	v_lshlrev_b32_e32 v72, 16, v143
	v_and_b32_e32 v73, 0xffff0000, v143
	v_pk_fma_f32 v[72:73], v[102:103], v[72:73], v[98:99]
	v_lshlrev_b32_e32 v82, 16, v169
	v_and_b32_e32 v83, 0xffff0000, v169
	v_pk_fma_f32 v[72:73], v[94:95], v[84:85], v[72:73]
	v_cndmask_b32_e64 v84, v138, v165, s[6:7]
	v_pk_fma_f32 v[72:73], v[90:91], v[82:83], v[72:73]
	s_nop 0
	s_nop 0
	v_mul_f32_e32 v82, 0xbfb8aa3b, v72
	v_mul_f32_e32 v83, 0xbfb8aa3b, v73
	v_exp_f32_e32 v82, v82
	v_exp_f32_e32 v83, v83
	v_add_f32_e32 v82, 1.0, v82
	v_add_f32_e32 v83, 1.0, v83
	v_rcp_f32_e32 v82, v82
	v_rcp_f32_e32 v83, v83
	s_nop 0
	v_pk_mul_f32 v[72:73], v[72:73], v[82:83]
	s_nop 0
	v_pk_mul_f32 v[82:83], v[74:75], v[72:73]
	v_cvt_pk_bf16_f32 v72, v76, v77
	v_mad_i64_i32 v[76:77], s[0:1], v106, s26, v[172:173]
	v_cvt_pk_bf16_f32 v73, v78, v79
	v_cvt_pk_bf16_f32 v74, v80, v81
	v_cvt_pk_bf16_f32 v75, v82, v83
	v_lshl_add_u64 v[132:133], v[76:77], 0, v[204:205]
	global_store_dwordx4 v[132:133], v[72:75], off
	ds_bpermute_b32 v72, v193, v128
	ds_bpermute_b32 v73, v193, v129
	ds_bpermute_b32 v74, v193, v130
	ds_bpermute_b32 v75, v193, v131
	v_cndmask_b32_e64 v77, v107, v168, s[6:7]
	s_waitcnt lgkmcnt(3)
	v_cndmask_b32_e64 v76, v72, v86, s[4:5]
	s_waitcnt lgkmcnt(2)
	v_cndmask_b32_e64 v79, v73, v87, s[4:5]
	v_lshlrev_b32_e32 v72, 16, v76
	v_and_b32_e32 v73, 0xffff0000, v76
	s_waitcnt lgkmcnt(1)
	v_cndmask_b32_e64 v81, v74, v104, s[4:5]
	s_waitcnt lgkmcnt(0)
	v_cndmask_b32_e64 v83, v75, v105, s[4:5]
	v_lshlrev_b32_e32 v74, 16, v77
	v_and_b32_e32 v75, 0xffff0000, v77
	v_pk_fma_f32 v[72:73], v[120:121], v[72:73], v[116:117]
	v_lshlrev_b32_e32 v76, 16, v128
	v_and_b32_e32 v77, 0xffff0000, v128
	v_pk_fma_f32 v[72:73], v[112:113], v[76:77], v[72:73]
	v_cndmask_b32_e64 v80, v136, v167, s[6:7]
	v_pk_fma_f32 v[72:73], v[108:109], v[74:75], v[72:73]
	v_lshlrev_b32_e32 v76, 16, v129
	v_and_b32_e32 v77, 0xffff0000, v129
	v_mul_f32_e32 v74, 0xbfb8aa3b, v72
	v_mul_f32_e32 v75, 0xbfb8aa3b, v73
	v_exp_f32_e32 v74, v74
	v_exp_f32_e32 v75, v75
	v_cndmask_b32_e64 v82, v137, v166, s[6:7]
	v_or_b32_e32 v78, 48, v164
	v_add_f32_e32 v74, 1.0, v74
	v_add_f32_e32 v75, 1.0, v75
	v_rcp_f32_e32 v74, v74
	v_rcp_f32_e32 v75, v75
	s_nop 0
	v_pk_mul_f32 v[72:73], v[72:73], v[74:75]
	s_nop 0
	v_pk_mul_f32 v[68:69], v[68:69], v[72:73]
	v_lshlrev_b32_e32 v72, 16, v79
	v_and_b32_e32 v73, 0xffff0000, v79
	v_pk_fma_f32 v[72:73], v[122:123], v[72:73], v[118:119]
	v_lshlrev_b32_e32 v74, 16, v80
	v_and_b32_e32 v75, 0xffff0000, v80
	v_pk_fma_f32 v[72:73], v[114:115], v[76:77], v[72:73]
	v_lshlrev_b32_e32 v76, 16, v130
	v_pk_fma_f32 v[72:73], v[110:111], v[74:75], v[72:73]
	v_and_b32_e32 v77, 0xffff0000, v130
	s_nop 0
	v_mul_f32_e32 v74, 0xbfb8aa3b, v72
	v_mul_f32_e32 v75, 0xbfb8aa3b, v73
	v_exp_f32_e32 v74, v74
	v_exp_f32_e32 v75, v75
	v_add_f32_e32 v74, 1.0, v74
	v_add_f32_e32 v75, 1.0, v75
	v_rcp_f32_e32 v74, v74
	v_rcp_f32_e32 v75, v75
	s_nop 0
	v_pk_mul_f32 v[72:73], v[72:73], v[74:75]
	s_nop 0
	v_pk_mul_f32 v[70:71], v[70:71], v[72:73]
	v_lshlrev_b32_e32 v72, 16, v81
	v_and_b32_e32 v73, 0xffff0000, v81
	v_pk_fma_f32 v[72:73], v[100:101], v[72:73], v[96:97]
	v_lshlrev_b32_e32 v74, 16, v82
	v_and_b32_e32 v75, 0xffff0000, v82
	v_pk_fma_f32 v[72:73], v[92:93], v[76:77], v[72:73]
	v_lshlrev_b32_e32 v76, 16, v131
	v_pk_fma_f32 v[72:73], v[88:89], v[74:75], v[72:73]
	v_and_b32_e32 v77, 0xffff0000, v131
	s_nop 0
	v_mul_f32_e32 v74, 0xbfb8aa3b, v72
	v_mul_f32_e32 v75, 0xbfb8aa3b, v73
	v_exp_f32_e32 v74, v74
	v_exp_f32_e32 v75, v75
	v_add_f32_e32 v74, 1.0, v74
	v_add_f32_e32 v75, 1.0, v75
	v_rcp_f32_e32 v74, v74
	v_rcp_f32_e32 v75, v75
	s_nop 0
	v_pk_mul_f32 v[72:73], v[72:73], v[74:75]
	s_nop 0
	v_pk_mul_f32 v[72:73], v[64:65], v[72:73]
	v_lshlrev_b32_e32 v64, 16, v83
	v_and_b32_e32 v65, 0xffff0000, v83
	v_pk_fma_f32 v[64:65], v[102:103], v[64:65], v[98:99]
	v_lshlrev_b32_e32 v74, 16, v84
	v_and_b32_e32 v75, 0xffff0000, v84
	v_pk_fma_f32 v[64:65], v[94:95], v[76:77], v[64:65]
	s_nop 0
	v_pk_fma_f32 v[64:65], v[90:91], v[74:75], v[64:65]
	s_nop 0
	s_nop 0
	v_mul_f32_e32 v74, 0xbfb8aa3b, v64
	v_mul_f32_e32 v75, 0xbfb8aa3b, v65
	v_exp_f32_e32 v74, v74
	v_exp_f32_e32 v75, v75
	v_add_f32_e32 v74, 1.0, v74
	v_add_f32_e32 v75, 1.0, v75
	v_rcp_f32_e32 v74, v74
	v_rcp_f32_e32 v75, v75
	s_nop 0
	v_pk_mul_f32 v[64:65], v[64:65], v[74:75]
	s_nop 0
	v_pk_mul_f32 v[74:75], v[66:67], v[64:65]
	v_cvt_pk_bf16_f32 v64, v68, v69
	v_mad_i64_i32 v[68:69], s[0:1], v78, s26, v[172:173]
	v_cvt_pk_bf16_f32 v65, v70, v71
	v_cvt_pk_bf16_f32 v66, v72, v73
	v_cvt_pk_bf16_f32 v67, v74, v75
	v_lshl_add_u64 v[112:113], v[68:69], 0, v[204:205]
	global_store_dwordx4 v[112:113], v[64:67], off
	s_mov_b64 s[0:1], -1
	s_nop 0
	v_or_b32_e32 v64, 0x80, v192
	v_ashrrev_i32_e32 v65, 31, v64
	v_lshlrev_b64 v[64:65], 2, v[64:65]
	v_lshl_add_u64 v[66:67], s[46:47], 0, v[64:65]
	v_lshl_add_u64 v[72:73], s[48:49], 0, v[64:65]
	global_load_dwordx4 v[76:79], v[190:191], off offset:528
	global_load_dwordx4 v[92:95], v[190:191], off offset:512
	global_load_dwordx4 v[68:71], v[66:67], off offset:16
	global_load_dwordx4 v[84:87], v[66:67], off
	s_nop 0
	global_load_dwordx4 v[64:67], v[72:73], off offset:16
	global_load_dwordx4 v[80:83], v[72:73], off
	s_nop 0
	global_load_dwordx4 v[72:75], v[188:189], off offset:528
	global_load_dwordx4 v[88:91], v[188:189], off offset:512
	global_load_dwordx4 v[108:111], v[194:195], off offset:256
	global_load_dwordx4 v[104:107], v[198:199], off offset:256
	global_load_dwordx4 v[100:103], v[200:201], off offset:256
	global_load_dwordx4 v[96:99], v[206:207], off offset:256
	global_load_dwordx4 v[114:117], v[196:197], off offset:256
	global_load_dwordx4 v[118:121], v[202:203], off offset:256
	s_waitcnt vmcnt(5)
	ds_bpermute_b32 v130, v193, v108
	s_waitcnt vmcnt(4)
	ds_bpermute_b32 v136, v225, v104
	ds_bpermute_b32 v137, v225, v105
	ds_bpermute_b32 v134, v193, v110
	s_waitcnt vmcnt(1)
	v_cndmask_b32_e64 v122, v117, 0, s[62:63]
	v_cndmask_b32_e64 v123, v116, 0, s[62:63]
	s_waitcnt vmcnt(0)
	v_cndmask_b32_e64 v116, v119, 0, s[50:51]
	v_cndmask_b32_e64 v117, v118, 0, s[50:51]
	ds_bpermute_b32 v118, v225, v108
	ds_bpermute_b32 v119, v225, v109
	ds_bpermute_b32 v135, v193, v111
	v_cndmask_b32_e64 v128, v115, 0, s[62:63]
	v_cndmask_b32_e64 v129, v114, 0, s[62:63]
	v_cndmask_b32_e64 v114, v121, 0, s[50:51]
	v_cndmask_b32_e64 v115, v120, 0, s[50:51]
	ds_bpermute_b32 v120, v225, v110
	ds_bpermute_b32 v121, v225, v111
	ds_bpermute_b32 v138, v225, v106
	ds_bpermute_b32 v139, v225, v107
	s_waitcnt lgkmcnt(10)
	v_cndmask_b32_e64 v129, v130, v129, s[4:5]
	s_waitcnt lgkmcnt(6)
	v_cndmask_b32_e64 v140, v118, v136, s[6:7]
	s_waitcnt lgkmcnt(5)
	v_cndmask_b32_e64 v141, v119, v137, s[6:7]
	v_lshlrev_b32_e32 v118, 16, v129
	v_and_b32_e32 v119, 0xffff0000, v129
	v_cndmask_b32_e64 v142, v134, v123, s[4:5]
	s_waitcnt lgkmcnt(4)
	v_cndmask_b32_e64 v164, v135, v122, s[4:5]
	v_pk_fma_f32 v[118:119], v[92:93], v[118:119], v[88:89]
	v_lshlrev_b32_e32 v122, 16, v108
	v_and_b32_e32 v123, 0xffff0000, v108
	s_waitcnt lgkmcnt(1)
	v_cndmask_b32_e64 v143, v120, v138, s[6:7]
	s_waitcnt lgkmcnt(0)
	v_cndmask_b32_e64 v165, v121, v139, s[6:7]
	v_lshlrev_b32_e32 v120, 16, v140
	v_and_b32_e32 v121, 0xffff0000, v140
	v_pk_fma_f32 v[118:119], v[84:85], v[122:123], v[118:119]
	ds_bpermute_b32 v131, v193, v109
	v_pk_fma_f32 v[118:119], v[80:81], v[120:121], v[118:119]
	s_waitcnt lgkmcnt(0)
	v_cndmask_b32_e64 v128, v131, v128, s[4:5]
	s_nop 0
	v_mul_f32_e32 v108, 0xbfb8aa3b, v118
	v_exp_f32_e32 v108, v108
	s_nop 0
	v_add_f32_e32 v108, 1.0, v108
	v_rcp_f32_e32 v120, v108
	v_mul_f32_e32 v108, 0xbfb8aa3b, v119
	v_exp_f32_e32 v108, v108
	s_nop 0
	v_add_f32_e32 v108, 1.0, v108
	v_rcp_f32_e32 v121, v108
	v_lshlrev_b32_e32 v108, 16, v109
	v_and_b32_e32 v109, 0xffff0000, v109
	v_pk_mul_f32 v[118:119], v[118:119], v[120:121]
	s_nop 0
	v_pk_mul_f32 v[60:61], v[60:61], v[118:119]
	v_lshlrev_b32_e32 v118, 16, v128
	v_and_b32_e32 v119, 0xffff0000, v128
	v_pk_mul_f32 v[118:119], v[94:95], v[118:119]
	v_lshlrev_b32_e32 v120, 16, v141
	v_and_b32_e32 v121, 0xffff0000, v141
	v_pk_fma_f32 v[108:109], v[86:87], v[108:109], v[118:119]
	s_nop 0
	v_pk_fma_f32 v[108:109], v[82:83], v[120:121], v[108:109]
	v_lshlrev_b32_e32 v120, 16, v110
	v_pk_add_f32 v[108:109], v[90:91], v[108:109]
	v_and_b32_e32 v121, 0xffff0000, v110
	v_mul_f32_e32 v118, 0xbfb8aa3b, v108
	v_mul_f32_e32 v119, 0xbfb8aa3b, v109
	v_exp_f32_e32 v118, v118
	v_exp_f32_e32 v119, v119
	v_add_f32_e32 v118, 1.0, v118
	v_add_f32_e32 v119, 1.0, v119
	v_rcp_f32_e32 v118, v118
	v_rcp_f32_e32 v119, v119
	s_nop 0
	v_pk_mul_f32 v[108:109], v[108:109], v[118:119]
	s_nop 0
	v_pk_mul_f32 v[62:63], v[62:63], v[108:109]
	v_lshlrev_b32_e32 v108, 16, v142
	v_and_b32_e32 v109, 0xffff0000, v142
	v_pk_fma_f32 v[108:109], v[76:77], v[108:109], v[72:73]
	v_lshlrev_b32_e32 v118, 16, v143
	v_and_b32_e32 v119, 0xffff0000, v143
	v_pk_fma_f32 v[108:109], v[68:69], v[120:121], v[108:109]
	s_nop 0
	v_pk_fma_f32 v[108:109], v[64:65], v[118:119], v[108:109]
	s_nop 0
	s_nop 0
	v_mul_f32_e32 v110, 0xbfb8aa3b, v108
	v_exp_f32_e32 v110, v110
	s_nop 0
	v_add_f32_e32 v110, 1.0, v110
	v_rcp_f32_e32 v118, v110
	v_mul_f32_e32 v110, 0xbfb8aa3b, v109
	v_exp_f32_e32 v110, v110
	s_nop 0
	v_add_f32_e32 v110, 1.0, v110
	v_rcp_f32_e32 v119, v110
	v_lshlrev_b32_e32 v110, 16, v111
	v_and_b32_e32 v111, 0xffff0000, v111
	v_pk_mul_f32 v[108:109], v[108:109], v[118:119]
	s_nop 0
	v_pk_mul_f32 v[108:109], v[56:57], v[108:109]
	v_lshlrev_b32_e32 v56, 16, v164
	v_and_b32_e32 v57, 0xffff0000, v164
	v_pk_fma_f32 v[56:57], v[78:79], v[56:57], v[74:75]
	v_lshlrev_b32_e32 v118, 16, v165
	v_and_b32_e32 v119, 0xffff0000, v165
	v_pk_fma_f32 v[56:57], v[70:71], v[110:111], v[56:57]
	s_nop 0
	v_pk_fma_f32 v[56:57], v[66:67], v[118:119], v[56:57]
	ds_bpermute_b32 v118, v225, v102
	ds_bpermute_b32 v119, v225, v103
	v_mul_f32_e32 v110, 0xbfb8aa3b, v56
	v_mul_f32_e32 v111, 0xbfb8aa3b, v57
	v_exp_f32_e32 v110, v110
	v_exp_f32_e32 v111, v111
	s_waitcnt lgkmcnt(1)
	v_cndmask_b32_e64 v123, v138, v118, s[6:7]
	s_waitcnt lgkmcnt(0)
	v_cndmask_b32_e64 v129, v139, v119, s[6:7]
	v_add_f32_e32 v110, 1.0, v110
	v_add_f32_e32 v111, 1.0, v111
	v_rcp_f32_e32 v110, v110
	v_rcp_f32_e32 v111, v111
	s_nop 0
	v_pk_mul_f32 v[56:57], v[56:57], v[110:111]
	s_nop 0
	v_pk_mul_f32 v[110:111], v[58:59], v[56:57]
	v_cvt_pk_bf16_f32 v57, v62, v63
	ds_bpermute_b32 v62, v193, v104
	v_cvt_pk_bf16_f32 v59, v110, v111
	ds_bpermute_b32 v110, v225, v100
	v_cvt_pk_bf16_f32 v56, v60, v61
	v_cvt_pk_bf16_f32 v58, v108, v109
	global_store_dwordx4 v[156:157], v[56:59], off offset:256
	v_lshlrev_b32_e32 v60, 16, v104
	v_and_b32_e32 v61, 0xffff0000, v104
	s_waitcnt lgkmcnt(1)
	v_cndmask_b32_e64 v57, v62, v130, s[4:5]
	v_lshlrev_b32_e32 v56, 16, v57
	v_and_b32_e32 v57, 0xffff0000, v57
	s_waitcnt lgkmcnt(0)
	v_cndmask_b32_e64 v59, v136, v110, s[6:7]
	v_pk_fma_f32 v[56:57], v[92:93], v[56:57], v[88:89]
	v_lshlrev_b32_e32 v58, 16, v59
	v_and_b32_e32 v59, 0xffff0000, v59
	v_pk_fma_f32 v[56:57], v[84:85], v[60:61], v[56:57]
	ds_bpermute_b32 v63, v193, v105
	v_pk_fma_f32 v[56:57], v[80:81], v[58:59], v[56:57]
	ds_bpermute_b32 v111, v225, v101
	v_lshlrev_b32_e32 v60, 16, v105
	v_mul_f32_e32 v58, 0xbfb8aa3b, v56
	v_mul_f32_e32 v59, 0xbfb8aa3b, v57
	v_exp_f32_e32 v58, v58
	v_exp_f32_e32 v59, v59
	s_waitcnt lgkmcnt(1)
	v_cndmask_b32_e64 v120, v63, v131, s[4:5]
	s_waitcnt lgkmcnt(0)
	v_cndmask_b32_e64 v121, v137, v111, s[6:7]
	v_add_f32_e32 v58, 1.0, v58
	v_add_f32_e32 v59, 1.0, v59
	v_rcp_f32_e32 v58, v58
	v_rcp_f32_e32 v59, v59
	v_and_b32_e32 v61, 0xffff0000, v105
	ds_bpermute_b32 v108, v193, v106
	ds_bpermute_b32 v109, v193, v107
	v_pk_mul_f32 v[56:57], v[56:57], v[58:59]
	v_lshlrev_b32_e32 v58, 16, v121
	v_pk_mul_f32 v[52:53], v[52:53], v[56:57]
	v_lshlrev_b32_e32 v56, 16, v120
	v_and_b32_e32 v57, 0xffff0000, v120
	v_pk_fma_f32 v[56:57], v[94:95], v[56:57], v[90:91]
	v_and_b32_e32 v59, 0xffff0000, v121
	v_pk_fma_f32 v[56:57], v[86:87], v[60:61], v[56:57]
	s_waitcnt lgkmcnt(1)
	v_cndmask_b32_e64 v122, v108, v134, s[4:5]
	v_pk_fma_f32 v[56:57], v[82:83], v[58:59], v[56:57]
	v_lshlrev_b32_e32 v60, 16, v106
	v_and_b32_e32 v61, 0xffff0000, v106
	v_mul_f32_e32 v58, 0xbfb8aa3b, v56
	v_mul_f32_e32 v59, 0xbfb8aa3b, v57
	v_exp_f32_e32 v58, v58
	v_exp_f32_e32 v59, v59
	s_waitcnt lgkmcnt(0)
	v_cndmask_b32_e64 v128, v109, v135, s[4:5]
	v_add_f32_e32 v58, 1.0, v58
	v_add_f32_e32 v59, 1.0, v59
	v_rcp_f32_e32 v58, v58
	v_rcp_f32_e32 v59, v59
	s_nop 0
	v_pk_mul_f32 v[56:57], v[56:57], v[58:59]
	s_nop 0
	v_pk_mul_f32 v[54:55], v[54:55], v[56:57]
	v_lshlrev_b32_e32 v56, 16, v122
	v_and_b32_e32 v57, 0xffff0000, v122
	v_pk_fma_f32 v[56:57], v[76:77], v[56:57], v[72:73]
	v_lshlrev_b32_e32 v58, 16, v123
	v_and_b32_e32 v59, 0xffff0000, v123
	v_pk_fma_f32 v[56:57], v[68:69], v[60:61], v[56:57]
	v_lshlrev_b32_e32 v60, 16, v107
	v_pk_fma_f32 v[56:57], v[64:65], v[58:59], v[56:57]
	v_and_b32_e32 v61, 0xffff0000, v107
	s_nop 0
	v_mul_f32_e32 v58, 0xbfb8aa3b, v56
	v_mul_f32_e32 v59, 0xbfb8aa3b, v57
	v_exp_f32_e32 v58, v58
	v_exp_f32_e32 v59, v59
	v_add_f32_e32 v58, 1.0, v58
	v_add_f32_e32 v59, 1.0, v59
	v_rcp_f32_e32 v58, v58
	v_rcp_f32_e32 v59, v59
	s_nop 0
	v_pk_mul_f32 v[56:57], v[56:57], v[58:59]
	s_nop 0
	v_pk_mul_f32 v[56:57], v[48:49], v[56:57]
	v_lshlrev_b32_e32 v48, 16, v128
	v_and_b32_e32 v49, 0xffff0000, v128
	v_pk_fma_f32 v[48:49], v[78:79], v[48:49], v[74:75]
	v_lshlrev_b32_e32 v58, 16, v129
	v_and_b32_e32 v59, 0xffff0000, v129
	v_pk_fma_f32 v[48:49], v[70:71], v[60:61], v[48:49]
	ds_bpermute_b32 v60, v225, v98
	v_pk_fma_f32 v[48:49], v[66:67], v[58:59], v[48:49]
	ds_bpermute_b32 v61, v225, v99
	s_waitcnt lgkmcnt(1)
	v_cndmask_b32_e64 v105, v118, v60, s[6:7]
	v_mul_f32_e32 v58, 0xbfb8aa3b, v48
	v_mul_f32_e32 v59, 0xbfb8aa3b, v49
	v_exp_f32_e32 v58, v58
	v_exp_f32_e32 v59, v59
	s_waitcnt lgkmcnt(0)
	v_cndmask_b32_e64 v107, v119, v61, s[6:7]
	v_add_f32_e32 v58, 1.0, v58
	v_add_f32_e32 v59, 1.0, v59
	v_rcp_f32_e32 v58, v58
	v_rcp_f32_e32 v59, v59
	s_nop 0
	v_pk_mul_f32 v[48:49], v[48:49], v[58:59]
	s_nop 0
	v_pk_mul_f32 v[58:59], v[50:51], v[48:49]
	v_cvt_pk_bf16_f32 v49, v54, v55
	ds_bpermute_b32 v54, v193, v100
	v_cvt_pk_bf16_f32 v51, v58, v59
	ds_bpermute_b32 v58, v225, v96
	v_cvt_pk_bf16_f32 v48, v52, v53
	v_cvt_pk_bf16_f32 v50, v56, v57
	global_store_dwordx4 v[146:147], v[48:51], off offset:256
	v_lshlrev_b32_e32 v52, 16, v100
	v_and_b32_e32 v53, 0xffff0000, v100
	s_waitcnt lgkmcnt(1)
	v_cndmask_b32_e64 v49, v54, v62, s[4:5]
	v_lshlrev_b32_e32 v48, 16, v49
	v_and_b32_e32 v49, 0xffff0000, v49
	s_waitcnt lgkmcnt(0)
	v_cndmask_b32_e64 v51, v110, v58, s[6:7]
	v_pk_fma_f32 v[48:49], v[92:93], v[48:49], v[88:89]
	v_lshlrev_b32_e32 v50, 16, v51
	v_and_b32_e32 v51, 0xffff0000, v51
	v_pk_fma_f32 v[48:49], v[84:85], v[52:53], v[48:49]
	ds_bpermute_b32 v55, v193, v101
	v_pk_fma_f32 v[48:49], v[80:81], v[50:51], v[48:49]
	ds_bpermute_b32 v59, v225, v97
	v_lshlrev_b32_e32 v52, 16, v101
	v_mul_f32_e32 v50, 0xbfb8aa3b, v48
	v_mul_f32_e32 v51, 0xbfb8aa3b, v49
	v_exp_f32_e32 v50, v50
	v_exp_f32_e32 v51, v51
	s_waitcnt lgkmcnt(1)
	v_cndmask_b32_e64 v62, v55, v63, s[4:5]
	s_waitcnt lgkmcnt(0)
	v_cndmask_b32_e64 v63, v111, v59, s[6:7]
	v_add_f32_e32 v50, 1.0, v50
	v_add_f32_e32 v51, 1.0, v51
	v_rcp_f32_e32 v50, v50
	v_rcp_f32_e32 v51, v51
	v_and_b32_e32 v53, 0xffff0000, v101
	ds_bpermute_b32 v56, v193, v102
	ds_bpermute_b32 v57, v193, v103
	v_pk_mul_f32 v[48:49], v[48:49], v[50:51]
	v_lshlrev_b32_e32 v50, 16, v63
	v_pk_mul_f32 v[44:45], v[44:45], v[48:49]
	v_lshlrev_b32_e32 v48, 16, v62
	v_and_b32_e32 v49, 0xffff0000, v62
	v_pk_fma_f32 v[48:49], v[94:95], v[48:49], v[90:91]
	v_and_b32_e32 v51, 0xffff0000, v63
	v_pk_fma_f32 v[48:49], v[86:87], v[52:53], v[48:49]
	s_waitcnt lgkmcnt(1)
	v_cndmask_b32_e64 v104, v56, v108, s[4:5]
	v_pk_fma_f32 v[48:49], v[82:83], v[50:51], v[48:49]
	v_lshlrev_b32_e32 v52, 16, v102
	v_and_b32_e32 v53, 0xffff0000, v102
	v_mul_f32_e32 v50, 0xbfb8aa3b, v48
	v_mul_f32_e32 v51, 0xbfb8aa3b, v49
	v_exp_f32_e32 v50, v50
	v_exp_f32_e32 v51, v51
	s_waitcnt lgkmcnt(0)
	v_cndmask_b32_e64 v106, v57, v109, s[4:5]
	v_add_f32_e32 v50, 1.0, v50
	v_add_f32_e32 v51, 1.0, v51
	v_rcp_f32_e32 v50, v50
	v_rcp_f32_e32 v51, v51
	s_nop 0
	v_pk_mul_f32 v[48:49], v[48:49], v[50:51]
	s_nop 0
	v_pk_mul_f32 v[46:47], v[46:47], v[48:49]
	v_lshlrev_b32_e32 v48, 16, v104
	v_and_b32_e32 v49, 0xffff0000, v104
	v_pk_fma_f32 v[48:49], v[76:77], v[48:49], v[72:73]
	v_lshlrev_b32_e32 v50, 16, v105
	v_and_b32_e32 v51, 0xffff0000, v105
	v_pk_fma_f32 v[48:49], v[68:69], v[52:53], v[48:49]
	v_lshlrev_b32_e32 v52, 16, v103
	v_pk_fma_f32 v[48:49], v[64:65], v[50:51], v[48:49]
	v_and_b32_e32 v53, 0xffff0000, v103
	s_nop 0
	v_mul_f32_e32 v50, 0xbfb8aa3b, v48
	v_mul_f32_e32 v51, 0xbfb8aa3b, v49
	v_exp_f32_e32 v50, v50
	v_exp_f32_e32 v51, v51
	v_add_f32_e32 v50, 1.0, v50
	v_add_f32_e32 v51, 1.0, v51
	v_rcp_f32_e32 v50, v50
	v_rcp_f32_e32 v51, v51
	s_nop 0
	v_pk_mul_f32 v[48:49], v[48:49], v[50:51]
	s_nop 0
	v_pk_mul_f32 v[48:49], v[40:41], v[48:49]
	v_lshlrev_b32_e32 v40, 16, v106
	v_and_b32_e32 v41, 0xffff0000, v106
	v_pk_fma_f32 v[40:41], v[78:79], v[40:41], v[74:75]
	v_lshlrev_b32_e32 v50, 16, v107
	v_and_b32_e32 v51, 0xffff0000, v107
	v_pk_fma_f32 v[40:41], v[70:71], v[52:53], v[40:41]
	s_nop 0
	v_pk_fma_f32 v[40:41], v[66:67], v[50:51], v[40:41]
	s_nop 0
	s_nop 0
	v_mul_f32_e32 v50, 0xbfb8aa3b, v40
	v_mul_f32_e32 v51, 0xbfb8aa3b, v41
	v_exp_f32_e32 v50, v50
	v_exp_f32_e32 v51, v51
	v_add_f32_e32 v50, 1.0, v50
	v_add_f32_e32 v51, 1.0, v51
	v_rcp_f32_e32 v50, v50
	v_rcp_f32_e32 v51, v51
	s_nop 0
	v_pk_mul_f32 v[40:41], v[40:41], v[50:51]
	s_nop 0
	v_pk_mul_f32 v[50:51], v[42:43], v[40:41]
	v_cvt_pk_bf16_f32 v40, v44, v45
	v_cvt_pk_bf16_f32 v41, v46, v47
	v_cvt_pk_bf16_f32 v42, v48, v49
	v_cvt_pk_bf16_f32 v43, v50, v51
	global_store_dwordx4 v[148:149], v[40:43], off offset:256
	ds_bpermute_b32 v40, v193, v96
	ds_bpermute_b32 v41, v193, v97
	ds_bpermute_b32 v42, v193, v98
	ds_bpermute_b32 v43, v193, v99
	v_cndmask_b32_e64 v45, v58, v117, s[6:7]
	s_waitcnt lgkmcnt(3)
	v_cndmask_b32_e64 v44, v40, v54, s[4:5]
	s_waitcnt lgkmcnt(2)
	v_cndmask_b32_e64 v46, v41, v55, s[4:5]
	v_lshlrev_b32_e32 v40, 16, v44
	v_and_b32_e32 v41, 0xffff0000, v44
	s_waitcnt lgkmcnt(1)
	v_cndmask_b32_e64 v48, v42, v56, s[4:5]
	s_waitcnt lgkmcnt(0)
	v_cndmask_b32_e64 v50, v43, v57, s[4:5]
	v_lshlrev_b32_e32 v42, 16, v45
	v_and_b32_e32 v43, 0xffff0000, v45
	v_pk_fma_f32 v[40:41], v[92:93], v[40:41], v[88:89]
	v_lshlrev_b32_e32 v44, 16, v96
	v_and_b32_e32 v45, 0xffff0000, v96
	v_pk_fma_f32 v[40:41], v[84:85], v[44:45], v[40:41]
	v_cndmask_b32_e64 v47, v59, v116, s[6:7]
	v_pk_fma_f32 v[40:41], v[80:81], v[42:43], v[40:41]
	v_lshlrev_b32_e32 v44, 16, v97
	v_and_b32_e32 v45, 0xffff0000, v97
	v_mul_f32_e32 v42, 0xbfb8aa3b, v40
	v_mul_f32_e32 v43, 0xbfb8aa3b, v41
	v_exp_f32_e32 v42, v42
	v_exp_f32_e32 v43, v43
	v_cndmask_b32_e64 v49, v60, v115, s[6:7]
	v_cndmask_b32_e64 v51, v61, v114, s[6:7]
	v_add_f32_e32 v42, 1.0, v42
	v_add_f32_e32 v43, 1.0, v43
	v_rcp_f32_e32 v42, v42
	v_rcp_f32_e32 v43, v43
	s_nop 0
	v_pk_mul_f32 v[40:41], v[40:41], v[42:43]
	s_nop 0
	v_pk_mul_f32 v[36:37], v[36:37], v[40:41]
	v_lshlrev_b32_e32 v40, 16, v46
	v_and_b32_e32 v41, 0xffff0000, v46
	v_pk_fma_f32 v[40:41], v[94:95], v[40:41], v[90:91]
	v_lshlrev_b32_e32 v42, 16, v47
	v_and_b32_e32 v43, 0xffff0000, v47
	v_pk_fma_f32 v[40:41], v[86:87], v[44:45], v[40:41]
	v_lshlrev_b32_e32 v44, 16, v98
	v_pk_fma_f32 v[40:41], v[82:83], v[42:43], v[40:41]
	v_and_b32_e32 v45, 0xffff0000, v98
	s_nop 0
	v_mul_f32_e32 v42, 0xbfb8aa3b, v40
	v_mul_f32_e32 v43, 0xbfb8aa3b, v41
	v_exp_f32_e32 v42, v42
	v_exp_f32_e32 v43, v43
	v_add_f32_e32 v42, 1.0, v42
	v_add_f32_e32 v43, 1.0, v43
	v_rcp_f32_e32 v42, v42
	v_rcp_f32_e32 v43, v43
	s_nop 0
	v_pk_mul_f32 v[40:41], v[40:41], v[42:43]
	s_nop 0
	v_pk_mul_f32 v[38:39], v[38:39], v[40:41]
	v_lshlrev_b32_e32 v40, 16, v48
	v_and_b32_e32 v41, 0xffff0000, v48
	v_pk_fma_f32 v[40:41], v[76:77], v[40:41], v[72:73]
	v_lshlrev_b32_e32 v42, 16, v49
	v_and_b32_e32 v43, 0xffff0000, v49
	v_pk_fma_f32 v[40:41], v[68:69], v[44:45], v[40:41]
	v_lshlrev_b32_e32 v44, 16, v99
	v_pk_fma_f32 v[40:41], v[64:65], v[42:43], v[40:41]
	v_and_b32_e32 v45, 0xffff0000, v99
	s_nop 0
	v_mul_f32_e32 v42, 0xbfb8aa3b, v40
	v_mul_f32_e32 v43, 0xbfb8aa3b, v41
	v_exp_f32_e32 v42, v42
	v_exp_f32_e32 v43, v43
	v_add_f32_e32 v42, 1.0, v42
	v_add_f32_e32 v43, 1.0, v43
	v_rcp_f32_e32 v42, v42
	v_rcp_f32_e32 v43, v43
	s_nop 0
	v_pk_mul_f32 v[40:41], v[40:41], v[42:43]
	s_nop 0
	v_pk_mul_f32 v[40:41], v[32:33], v[40:41]
	v_lshlrev_b32_e32 v32, 16, v50
	v_and_b32_e32 v33, 0xffff0000, v50
	v_pk_fma_f32 v[32:33], v[78:79], v[32:33], v[74:75]
	v_lshlrev_b32_e32 v42, 16, v51
	v_and_b32_e32 v43, 0xffff0000, v51
	v_pk_fma_f32 v[32:33], v[70:71], v[44:45], v[32:33]
	s_nop 0
	v_pk_fma_f32 v[32:33], v[66:67], v[42:43], v[32:33]
	s_nop 0
	s_nop 0
	v_mul_f32_e32 v42, 0xbfb8aa3b, v32
	v_mul_f32_e32 v43, 0xbfb8aa3b, v33
	v_exp_f32_e32 v42, v42
	v_exp_f32_e32 v43, v43
	v_add_f32_e32 v42, 1.0, v42
	v_add_f32_e32 v43, 1.0, v43
	v_rcp_f32_e32 v42, v42
	v_rcp_f32_e32 v43, v43
	s_nop 0
	v_pk_mul_f32 v[32:33], v[32:33], v[42:43]
	s_nop 0
	v_pk_mul_f32 v[42:43], v[34:35], v[32:33]
	v_cvt_pk_bf16_f32 v32, v36, v37
	v_cvt_pk_bf16_f32 v33, v38, v39
	v_cvt_pk_bf16_f32 v34, v40, v41
	v_cvt_pk_bf16_f32 v35, v42, v43
	global_store_dwordx4 v[144:145], v[32:35], off offset:256
	global_load_dwordx4 v[48:51], v[150:151], off offset:256
	global_load_dwordx4 v[44:47], v[152:153], off offset:256
	global_load_dwordx4 v[40:43], v[154:155], off offset:256
	global_load_dwordx4 v[32:35], v[158:159], off offset:256
	global_load_dwordx4 v[52:55], v[162:163], off offset:256
	global_load_dwordx4 v[36:39], v[160:161], off offset:256
	s_waitcnt vmcnt(5)
	ds_bpermute_b32 v58, v193, v48
	ds_bpermute_b32 v56, v225, v48
	ds_bpermute_b32 v59, v193, v49
	s_waitcnt vmcnt(4)
	ds_bpermute_b32 v96, v225, v44
	ds_bpermute_b32 v57, v225, v49
	ds_bpermute_b32 v60, v193, v50
	ds_bpermute_b32 v62, v193, v51
	ds_bpermute_b32 v97, v225, v45
	s_waitcnt vmcnt(1)
	v_cndmask_b32_e64 v52, v52, 0, s[22:23]
	v_cndmask_b32_e64 v53, v53, 0, s[22:23]
	s_waitcnt lgkmcnt(7)
	v_cndmask_b32_e64 v100, v58, v52, s[4:5]
	v_cndmask_b32_e64 v55, v55, 0, s[22:23]
	v_cndmask_b32_e64 v54, v54, 0, s[22:23]
	s_waitcnt lgkmcnt(4)
	v_cndmask_b32_e64 v56, v56, v96, s[6:7]
	v_cndmask_b32_e64 v101, v59, v53, s[4:5]
	v_lshlrev_b32_e32 v52, 16, v100
	v_and_b32_e32 v53, 0xffff0000, v100
	s_waitcnt lgkmcnt(0)
	v_cndmask_b32_e64 v102, v57, v97, s[6:7]
	v_cndmask_b32_e64 v103, v60, v54, s[4:5]
	v_cndmask_b32_e64 v104, v62, v55, s[4:5]
	v_lshlrev_b32_e32 v54, 16, v56
	v_and_b32_e32 v55, 0xffff0000, v56
	v_pk_fma_f32 v[52:53], v[92:93], v[52:53], v[88:89]
	v_lshlrev_b32_e32 v56, 16, v48
	v_and_b32_e32 v57, 0xffff0000, v48
	v_pk_fma_f32 v[52:53], v[84:85], v[56:57], v[52:53]
	ds_bpermute_b32 v61, v225, v50
	v_pk_fma_f32 v[52:53], v[80:81], v[54:55], v[52:53]
	ds_bpermute_b32 v98, v225, v46
	ds_bpermute_b32 v63, v225, v51
	v_mul_f32_e32 v48, 0xbfb8aa3b, v52
	v_exp_f32_e32 v48, v48
	s_waitcnt lgkmcnt(1)
	v_cndmask_b32_e64 v61, v61, v98, s[6:7]
	ds_bpermute_b32 v99, v225, v47
	v_add_f32_e32 v48, 1.0, v48
	v_rcp_f32_e32 v54, v48
	v_mul_f32_e32 v48, 0xbfb8aa3b, v53
	v_exp_f32_e32 v48, v48
	s_waitcnt lgkmcnt(0)
	v_cndmask_b32_e64 v63, v63, v99, s[6:7]
	v_add_f32_e32 v48, 1.0, v48
	v_rcp_f32_e32 v55, v48
	v_lshlrev_b32_e32 v48, 16, v49
	v_and_b32_e32 v49, 0xffff0000, v49
	v_pk_mul_f32 v[52:53], v[52:53], v[54:55]
	s_nop 0
	v_pk_mul_f32 v[28:29], v[28:29], v[52:53]
	v_lshlrev_b32_e32 v52, 16, v101
	v_and_b32_e32 v53, 0xffff0000, v101
	v_pk_mul_f32 v[52:53], v[94:95], v[52:53]
	v_lshlrev_b32_e32 v54, 16, v102
	v_and_b32_e32 v55, 0xffff0000, v102
	v_pk_fma_f32 v[48:49], v[86:87], v[48:49], v[52:53]
	s_nop 0
	v_pk_fma_f32 v[48:49], v[82:83], v[54:55], v[48:49]
	v_lshlrev_b32_e32 v54, 16, v50
	v_pk_add_f32 v[48:49], v[90:91], v[48:49]
	v_and_b32_e32 v55, 0xffff0000, v50
	v_mul_f32_e32 v52, 0xbfb8aa3b, v48
	v_mul_f32_e32 v53, 0xbfb8aa3b, v49
	v_exp_f32_e32 v52, v52
	v_exp_f32_e32 v53, v53
	v_add_f32_e32 v52, 1.0, v52
	v_add_f32_e32 v53, 1.0, v53
	v_rcp_f32_e32 v52, v52
	v_rcp_f32_e32 v53, v53
	s_nop 0
	v_pk_mul_f32 v[48:49], v[48:49], v[52:53]
	s_nop 0
	v_pk_mul_f32 v[30:31], v[30:31], v[48:49]
	v_lshlrev_b32_e32 v48, 16, v103
	v_and_b32_e32 v49, 0xffff0000, v103
	v_pk_fma_f32 v[48:49], v[76:77], v[48:49], v[72:73]
	v_lshlrev_b32_e32 v52, 16, v61
	v_and_b32_e32 v53, 0xffff0000, v61
	v_pk_fma_f32 v[48:49], v[68:69], v[54:55], v[48:49]
	s_nop 0
	v_pk_fma_f32 v[48:49], v[64:65], v[52:53], v[48:49]
	s_nop 0
	s_nop 0
	v_mul_f32_e32 v50, 0xbfb8aa3b, v48
	v_exp_f32_e32 v50, v50
	s_nop 0
	v_add_f32_e32 v50, 1.0, v50
	v_rcp_f32_e32 v52, v50
	v_mul_f32_e32 v50, 0xbfb8aa3b, v49
	v_exp_f32_e32 v50, v50
	s_nop 0
	v_add_f32_e32 v50, 1.0, v50
	v_rcp_f32_e32 v53, v50
	v_lshlrev_b32_e32 v50, 16, v51
	v_and_b32_e32 v51, 0xffff0000, v51
	v_pk_mul_f32 v[48:49], v[48:49], v[52:53]
	s_nop 0
	v_pk_mul_f32 v[48:49], v[24:25], v[48:49]
	v_lshlrev_b32_e32 v24, 16, v104
	v_and_b32_e32 v25, 0xffff0000, v104
	v_pk_fma_f32 v[24:25], v[78:79], v[24:25], v[74:75]
	v_lshlrev_b32_e32 v52, 16, v63
	v_and_b32_e32 v53, 0xffff0000, v63
	v_pk_fma_f32 v[24:25], v[70:71], v[50:51], v[24:25]
	s_nop 0
	v_pk_fma_f32 v[24:25], v[66:67], v[52:53], v[24:25]
	ds_bpermute_b32 v52, v225, v42
	ds_bpermute_b32 v53, v225, v43
	v_mul_f32_e32 v50, 0xbfb8aa3b, v24
	v_mul_f32_e32 v51, 0xbfb8aa3b, v25
	v_exp_f32_e32 v50, v50
	v_exp_f32_e32 v51, v51
	s_waitcnt lgkmcnt(1)
	v_cndmask_b32_e64 v57, v98, v52, s[6:7]
	v_add_f32_e32 v50, 1.0, v50
	v_add_f32_e32 v51, 1.0, v51
	v_rcp_f32_e32 v50, v50
	v_rcp_f32_e32 v51, v51
	s_nop 0
	v_pk_mul_f32 v[24:25], v[24:25], v[50:51]
	s_nop 0
	v_pk_mul_f32 v[50:51], v[26:27], v[24:25]
	v_cvt_pk_bf16_f32 v25, v30, v31
	ds_bpermute_b32 v30, v193, v44
	v_cvt_pk_bf16_f32 v27, v50, v51
	ds_bpermute_b32 v50, v225, v40
	v_cvt_pk_bf16_f32 v24, v28, v29
	v_cvt_pk_bf16_f32 v26, v48, v49
	global_store_dwordx4 v[124:125], v[24:27], off offset:256
	v_lshlrev_b32_e32 v28, 16, v44
	v_and_b32_e32 v29, 0xffff0000, v44
	s_waitcnt lgkmcnt(1)
	v_cndmask_b32_e64 v25, v30, v58, s[4:5]
	v_lshlrev_b32_e32 v24, 16, v25
	v_and_b32_e32 v25, 0xffff0000, v25
	s_waitcnt lgkmcnt(0)
	v_cndmask_b32_e64 v27, v96, v50, s[6:7]
	v_pk_fma_f32 v[24:25], v[92:93], v[24:25], v[88:89]
	v_lshlrev_b32_e32 v26, 16, v27
	v_and_b32_e32 v27, 0xffff0000, v27
	v_pk_fma_f32 v[24:25], v[84:85], v[28:29], v[24:25]
	ds_bpermute_b32 v31, v193, v45
	v_pk_fma_f32 v[24:25], v[80:81], v[26:27], v[24:25]
	ds_bpermute_b32 v51, v225, v41
	v_lshlrev_b32_e32 v28, 16, v45
	v_mul_f32_e32 v26, 0xbfb8aa3b, v24
	v_mul_f32_e32 v27, 0xbfb8aa3b, v25
	v_exp_f32_e32 v26, v26
	v_exp_f32_e32 v27, v27
	s_waitcnt lgkmcnt(1)
	v_cndmask_b32_e64 v54, v31, v59, s[4:5]
	s_waitcnt lgkmcnt(0)
	v_cndmask_b32_e64 v55, v97, v51, s[6:7]
	v_add_f32_e32 v26, 1.0, v26
	v_add_f32_e32 v27, 1.0, v27
	v_rcp_f32_e32 v26, v26
	v_rcp_f32_e32 v27, v27
	v_and_b32_e32 v29, 0xffff0000, v45
	ds_bpermute_b32 v48, v193, v46
	ds_bpermute_b32 v49, v193, v47
	v_pk_mul_f32 v[24:25], v[24:25], v[26:27]
	v_lshlrev_b32_e32 v26, 16, v55
	v_pk_mul_f32 v[20:21], v[20:21], v[24:25]
	v_lshlrev_b32_e32 v24, 16, v54
	v_and_b32_e32 v25, 0xffff0000, v54
	v_pk_fma_f32 v[24:25], v[94:95], v[24:25], v[90:91]
	v_and_b32_e32 v27, 0xffff0000, v55
	v_pk_fma_f32 v[24:25], v[86:87], v[28:29], v[24:25]
	s_waitcnt lgkmcnt(1)
	v_cndmask_b32_e64 v56, v48, v60, s[4:5]
	v_pk_fma_f32 v[24:25], v[82:83], v[26:27], v[24:25]
	v_lshlrev_b32_e32 v28, 16, v46
	v_and_b32_e32 v29, 0xffff0000, v46
	v_mul_f32_e32 v26, 0xbfb8aa3b, v24
	v_mul_f32_e32 v27, 0xbfb8aa3b, v25
	v_exp_f32_e32 v26, v26
	v_exp_f32_e32 v27, v27
	s_waitcnt lgkmcnt(0)
	v_cndmask_b32_e64 v58, v49, v62, s[4:5]
	v_cndmask_b32_e64 v59, v99, v53, s[6:7]
	v_add_f32_e32 v26, 1.0, v26
	v_add_f32_e32 v27, 1.0, v27
	v_rcp_f32_e32 v26, v26
	v_rcp_f32_e32 v27, v27
	s_nop 0
	v_pk_mul_f32 v[24:25], v[24:25], v[26:27]
	s_nop 0
	v_pk_mul_f32 v[22:23], v[22:23], v[24:25]
	v_lshlrev_b32_e32 v24, 16, v56
	v_and_b32_e32 v25, 0xffff0000, v56
	v_pk_fma_f32 v[24:25], v[76:77], v[24:25], v[72:73]
	v_lshlrev_b32_e32 v26, 16, v57
	v_and_b32_e32 v27, 0xffff0000, v57
	v_pk_fma_f32 v[24:25], v[68:69], v[28:29], v[24:25]
	v_lshlrev_b32_e32 v28, 16, v47
	v_pk_fma_f32 v[24:25], v[64:65], v[26:27], v[24:25]
	v_and_b32_e32 v29, 0xffff0000, v47
	s_nop 0
	v_mul_f32_e32 v26, 0xbfb8aa3b, v24
	v_mul_f32_e32 v27, 0xbfb8aa3b, v25
	v_exp_f32_e32 v26, v26
	v_exp_f32_e32 v27, v27
	v_add_f32_e32 v26, 1.0, v26
	v_add_f32_e32 v27, 1.0, v27
	v_rcp_f32_e32 v26, v26
	v_rcp_f32_e32 v27, v27
	s_nop 0
	v_pk_mul_f32 v[24:25], v[24:25], v[26:27]
	s_nop 0
	v_pk_mul_f32 v[24:25], v[16:17], v[24:25]
	v_lshlrev_b32_e32 v16, 16, v58
	v_and_b32_e32 v17, 0xffff0000, v58
	v_pk_fma_f32 v[16:17], v[78:79], v[16:17], v[74:75]
	v_lshlrev_b32_e32 v26, 16, v59
	v_and_b32_e32 v27, 0xffff0000, v59
	v_pk_fma_f32 v[16:17], v[70:71], v[28:29], v[16:17]
	ds_bpermute_b32 v28, v225, v34
	v_pk_fma_f32 v[16:17], v[66:67], v[26:27], v[16:17]
	ds_bpermute_b32 v29, v225, v35
	s_waitcnt lgkmcnt(1)
	v_cndmask_b32_e64 v45, v52, v28, s[6:7]
	v_mul_f32_e32 v26, 0xbfb8aa3b, v16
	v_mul_f32_e32 v27, 0xbfb8aa3b, v17
	v_exp_f32_e32 v26, v26
	v_exp_f32_e32 v27, v27
	s_waitcnt lgkmcnt(0)
	v_cndmask_b32_e64 v47, v53, v29, s[6:7]
	v_add_f32_e32 v26, 1.0, v26
	v_add_f32_e32 v27, 1.0, v27
	v_rcp_f32_e32 v26, v26
	v_rcp_f32_e32 v27, v27
	s_nop 0
	v_pk_mul_f32 v[16:17], v[16:17], v[26:27]
	s_nop 0
	v_pk_mul_f32 v[26:27], v[18:19], v[16:17]
	v_cvt_pk_bf16_f32 v17, v22, v23
	ds_bpermute_b32 v22, v193, v40
	v_cvt_pk_bf16_f32 v19, v26, v27
	ds_bpermute_b32 v26, v225, v32
	v_cvt_pk_bf16_f32 v16, v20, v21
	v_cvt_pk_bf16_f32 v18, v24, v25
	global_store_dwordx4 v[126:127], v[16:19], off offset:256
	v_lshlrev_b32_e32 v20, 16, v40
	v_and_b32_e32 v21, 0xffff0000, v40
	s_waitcnt lgkmcnt(1)
	v_cndmask_b32_e64 v17, v22, v30, s[4:5]
	v_lshlrev_b32_e32 v16, 16, v17
	v_and_b32_e32 v17, 0xffff0000, v17
	s_waitcnt lgkmcnt(0)
	v_cndmask_b32_e64 v19, v50, v26, s[6:7]
	v_pk_fma_f32 v[16:17], v[92:93], v[16:17], v[88:89]
	v_lshlrev_b32_e32 v18, 16, v19
	v_and_b32_e32 v19, 0xffff0000, v19
	v_pk_fma_f32 v[16:17], v[84:85], v[20:21], v[16:17]
	ds_bpermute_b32 v23, v193, v41
	v_pk_fma_f32 v[16:17], v[80:81], v[18:19], v[16:17]
	ds_bpermute_b32 v27, v225, v33
	v_lshlrev_b32_e32 v20, 16, v41
	v_mul_f32_e32 v18, 0xbfb8aa3b, v16
	v_mul_f32_e32 v19, 0xbfb8aa3b, v17
	v_exp_f32_e32 v18, v18
	v_exp_f32_e32 v19, v19
	s_waitcnt lgkmcnt(1)
	v_cndmask_b32_e64 v30, v23, v31, s[4:5]
	s_waitcnt lgkmcnt(0)
	v_cndmask_b32_e64 v31, v51, v27, s[6:7]
	v_add_f32_e32 v18, 1.0, v18
	v_add_f32_e32 v19, 1.0, v19
	v_rcp_f32_e32 v18, v18
	v_rcp_f32_e32 v19, v19
	v_and_b32_e32 v21, 0xffff0000, v41
	ds_bpermute_b32 v24, v193, v42
	ds_bpermute_b32 v25, v193, v43
	v_pk_mul_f32 v[16:17], v[16:17], v[18:19]
	v_lshlrev_b32_e32 v18, 16, v31
	v_pk_mul_f32 v[12:13], v[12:13], v[16:17]
	v_lshlrev_b32_e32 v16, 16, v30
	v_and_b32_e32 v17, 0xffff0000, v30
	v_pk_fma_f32 v[16:17], v[94:95], v[16:17], v[90:91]
	v_and_b32_e32 v19, 0xffff0000, v31
	v_pk_fma_f32 v[16:17], v[86:87], v[20:21], v[16:17]
	s_waitcnt lgkmcnt(1)
	v_cndmask_b32_e64 v44, v24, v48, s[4:5]
	v_pk_fma_f32 v[16:17], v[82:83], v[18:19], v[16:17]
	v_lshlrev_b32_e32 v20, 16, v42
	v_and_b32_e32 v21, 0xffff0000, v42
	v_mul_f32_e32 v18, 0xbfb8aa3b, v16
	v_mul_f32_e32 v19, 0xbfb8aa3b, v17
	v_exp_f32_e32 v18, v18
	v_exp_f32_e32 v19, v19
	s_waitcnt lgkmcnt(0)
	v_cndmask_b32_e64 v46, v25, v49, s[4:5]
	v_add_f32_e32 v18, 1.0, v18
	v_add_f32_e32 v19, 1.0, v19
	v_rcp_f32_e32 v18, v18
	v_rcp_f32_e32 v19, v19
	s_nop 0
	v_pk_mul_f32 v[16:17], v[16:17], v[18:19]
	s_nop 0
	v_pk_mul_f32 v[14:15], v[14:15], v[16:17]
	v_lshlrev_b32_e32 v16, 16, v44
	v_and_b32_e32 v17, 0xffff0000, v44
	v_pk_fma_f32 v[16:17], v[76:77], v[16:17], v[72:73]
	v_lshlrev_b32_e32 v18, 16, v45
	v_and_b32_e32 v19, 0xffff0000, v45
	v_pk_fma_f32 v[16:17], v[68:69], v[20:21], v[16:17]
	v_lshlrev_b32_e32 v20, 16, v43
	v_pk_fma_f32 v[16:17], v[64:65], v[18:19], v[16:17]
	v_and_b32_e32 v21, 0xffff0000, v43
	s_nop 0
	v_mul_f32_e32 v18, 0xbfb8aa3b, v16
	v_mul_f32_e32 v19, 0xbfb8aa3b, v17
	v_exp_f32_e32 v18, v18
	v_exp_f32_e32 v19, v19
	v_add_f32_e32 v18, 1.0, v18
	v_add_f32_e32 v19, 1.0, v19
	v_rcp_f32_e32 v18, v18
	v_rcp_f32_e32 v19, v19
	s_nop 0
	v_pk_mul_f32 v[16:17], v[16:17], v[18:19]
	s_nop 0
	v_pk_mul_f32 v[16:17], v[8:9], v[16:17]
	v_lshlrev_b32_e32 v8, 16, v46
	v_and_b32_e32 v9, 0xffff0000, v46
	v_pk_fma_f32 v[8:9], v[78:79], v[8:9], v[74:75]
	v_lshlrev_b32_e32 v18, 16, v47
	v_and_b32_e32 v19, 0xffff0000, v47
	v_pk_fma_f32 v[8:9], v[70:71], v[20:21], v[8:9]
	s_nop 0
	v_pk_fma_f32 v[8:9], v[66:67], v[18:19], v[8:9]
	s_nop 0
	s_nop 0
	v_mul_f32_e32 v18, 0xbfb8aa3b, v8
	v_mul_f32_e32 v19, 0xbfb8aa3b, v9
	v_exp_f32_e32 v18, v18
	v_exp_f32_e32 v19, v19
	v_add_f32_e32 v18, 1.0, v18
	v_add_f32_e32 v19, 1.0, v19
	v_rcp_f32_e32 v18, v18
	v_rcp_f32_e32 v19, v19
	s_nop 0
	v_pk_mul_f32 v[8:9], v[8:9], v[18:19]
	s_nop 0
	v_pk_mul_f32 v[18:19], v[10:11], v[8:9]
	v_cvt_pk_bf16_f32 v8, v12, v13
	v_cvt_pk_bf16_f32 v9, v14, v15
	v_cvt_pk_bf16_f32 v10, v16, v17
	v_cvt_pk_bf16_f32 v11, v18, v19
	global_store_dwordx4 v[132:133], v[8:11], off offset:256
	ds_bpermute_b32 v8, v193, v32
	ds_bpermute_b32 v9, v193, v33
	ds_bpermute_b32 v10, v193, v34
	ds_bpermute_b32 v11, v193, v35
	s_waitcnt vmcnt(3)
	v_cndmask_b32_e64 v12, v39, 0, vcc
	s_waitcnt lgkmcnt(3)
	v_cndmask_b32_e64 v16, v8, v22, s[4:5]
	v_cndmask_b32_e64 v13, v38, 0, vcc
	v_cndmask_b32_e64 v15, v36, 0, vcc
	s_waitcnt lgkmcnt(2)
	v_cndmask_b32_e64 v17, v9, v23, s[4:5]
	v_lshlrev_b32_e32 v8, 16, v16
	v_and_b32_e32 v9, 0xffff0000, v16
	v_cndmask_b32_e64 v15, v26, v15, s[6:7]
	v_cndmask_b32_e64 v19, v28, v13, s[6:7]
	v_cndmask_b32_e64 v21, v29, v12, s[6:7]
	v_pk_fma_f32 v[8:9], v[92:93], v[8:9], v[88:89]
	v_lshlrev_b32_e32 v12, 16, v32
	v_and_b32_e32 v13, 0xffff0000, v32
	s_waitcnt lgkmcnt(1)
	v_cndmask_b32_e64 v18, v10, v24, s[4:5]
	s_waitcnt lgkmcnt(0)
	v_cndmask_b32_e64 v20, v11, v25, s[4:5]
	v_lshlrev_b32_e32 v10, 16, v15
	v_and_b32_e32 v11, 0xffff0000, v15
	v_pk_fma_f32 v[8:9], v[84:85], v[12:13], v[8:9]
	v_cndmask_b32_e64 v14, v37, 0, vcc
	v_pk_fma_f32 v[8:9], v[80:81], v[10:11], v[8:9]
	v_cndmask_b32_e64 v14, v27, v14, s[6:7]
	v_lshlrev_b32_e32 v12, 16, v33
	v_mul_f32_e32 v10, 0xbfb8aa3b, v8
	v_mul_f32_e32 v11, 0xbfb8aa3b, v9
	v_exp_f32_e32 v10, v10
	v_exp_f32_e32 v11, v11
	v_and_b32_e32 v13, 0xffff0000, v33
	s_andn2_b64 vcc, exec, s[68:69]
	v_add_f32_e32 v10, 1.0, v10
	v_add_f32_e32 v11, 1.0, v11
	v_rcp_f32_e32 v10, v10
	v_rcp_f32_e32 v11, v11
	s_nop 0
	v_pk_mul_f32 v[8:9], v[8:9], v[10:11]
	s_nop 0
	v_pk_mul_f32 v[4:5], v[4:5], v[8:9]
	v_lshlrev_b32_e32 v8, 16, v17
	v_and_b32_e32 v9, 0xffff0000, v17
	v_pk_fma_f32 v[8:9], v[94:95], v[8:9], v[90:91]
	v_lshlrev_b32_e32 v10, 16, v14
	v_and_b32_e32 v11, 0xffff0000, v14
	v_pk_fma_f32 v[8:9], v[86:87], v[12:13], v[8:9]
	v_lshlrev_b32_e32 v12, 16, v34
	v_pk_fma_f32 v[8:9], v[82:83], v[10:11], v[8:9]
	v_and_b32_e32 v13, 0xffff0000, v34
	s_nop 0
	v_mul_f32_e32 v10, 0xbfb8aa3b, v8
	v_mul_f32_e32 v11, 0xbfb8aa3b, v9
	v_exp_f32_e32 v10, v10
	v_exp_f32_e32 v11, v11
	v_add_f32_e32 v10, 1.0, v10
	v_add_f32_e32 v11, 1.0, v11
	v_rcp_f32_e32 v10, v10
	v_rcp_f32_e32 v11, v11
	s_nop 0
	v_pk_mul_f32 v[8:9], v[8:9], v[10:11]
	s_nop 0
	v_pk_mul_f32 v[6:7], v[6:7], v[8:9]
	v_lshlrev_b32_e32 v8, 16, v18
	v_and_b32_e32 v9, 0xffff0000, v18
	v_pk_fma_f32 v[8:9], v[76:77], v[8:9], v[72:73]
	v_lshlrev_b32_e32 v10, 16, v19
	v_and_b32_e32 v11, 0xffff0000, v19
	v_pk_fma_f32 v[8:9], v[68:69], v[12:13], v[8:9]
	v_lshlrev_b32_e32 v12, 16, v35
	v_pk_fma_f32 v[8:9], v[64:65], v[10:11], v[8:9]
	v_and_b32_e32 v13, 0xffff0000, v35
	s_nop 0
	v_mul_f32_e32 v10, 0xbfb8aa3b, v8
	v_mul_f32_e32 v11, 0xbfb8aa3b, v9
	v_exp_f32_e32 v10, v10
	v_exp_f32_e32 v11, v11
	v_add_f32_e32 v10, 1.0, v10
	v_add_f32_e32 v11, 1.0, v11
	v_rcp_f32_e32 v10, v10
	v_rcp_f32_e32 v11, v11
	s_nop 0
	v_pk_mul_f32 v[8:9], v[8:9], v[10:11]
	s_nop 0
	v_pk_mul_f32 v[8:9], v[0:1], v[8:9]
	v_lshlrev_b32_e32 v0, 16, v20
	v_and_b32_e32 v1, 0xffff0000, v20
	v_pk_fma_f32 v[0:1], v[78:79], v[0:1], v[74:75]
	v_lshlrev_b32_e32 v10, 16, v21
	v_and_b32_e32 v11, 0xffff0000, v21
	v_pk_fma_f32 v[0:1], v[70:71], v[12:13], v[0:1]
	s_nop 0
	v_pk_fma_f32 v[0:1], v[66:67], v[10:11], v[0:1]
	s_nop 0
	s_nop 0
	v_mul_f32_e32 v10, 0xbfb8aa3b, v0
	v_mul_f32_e32 v11, 0xbfb8aa3b, v1
	v_exp_f32_e32 v10, v10
	v_exp_f32_e32 v11, v11
	v_add_f32_e32 v10, 1.0, v10
	v_add_f32_e32 v11, 1.0, v11
	v_rcp_f32_e32 v10, v10
	v_rcp_f32_e32 v11, v11
	s_nop 0
	v_pk_mul_f32 v[0:1], v[0:1], v[10:11]
	s_nop 0
	v_pk_mul_f32 v[10:11], v[2:3], v[0:1]
	v_cvt_pk_bf16_f32 v0, v4, v5
	v_cvt_pk_bf16_f32 v1, v6, v7
	v_cvt_pk_bf16_f32 v2, v8, v9
	v_cvt_pk_bf16_f32 v3, v10, v11
	global_store_dwordx4 v[112:113], v[0:3], off offset:256
	s_cbranch_vccnz .LBB0_1053
	s_andn2_b64 vcc, exec, s[36:37]
	s_cbranch_vccnz .LBB0_1052
	s_barrier
	s_branch .LBB0_1052

.LBB0_1067:
	v_ashrrev_i32_e32 v6, 6, v4
	v_mov_b64_e32 v[8:9], s[10:11]
	v_mov_b64_e32 v[10:11], s[16:17]
	v_cmp_gt_i32_e32 vcc, s77, v6
	v_mov_b32_e32 v2, 0x7ff
	v_mov_b32_e32 v7, 0xfff
	v_mad_i64_i32 v[8:9], s[4:5], v6, s20, v[8:9]
	v_mad_i64_i32 v[38:39], s[4:5], v6, s20, v[10:11]
	v_and_b32_e32 v0, 0x1f8, v5
	v_add_u32_e32 v4, s2, v4
	v_cndmask_b32_e32 v13, v2, v7, vcc
	s_mov_b32 s4, 0x17ffff
	v_or_b32_e32 v12, 0x1400, v0
	v_ashrrev_i32_e32 v7, 31, v6
	v_lshlrev_b32_e32 v2, 1, v0
	v_cmp_lt_i32_e32 vcc, s4, v4
	v_and_b32_e32 v0, v13, v6
	v_lshlrev_b32_e32 v176, 1, v12
	v_lshlrev_b64 v[6:7], 10, v[6:7]
	s_or_b64 s[22:23], vcc, s[22:23]
	v_cmp_eq_u32_e32 vcc, 0, v0
	v_cmp_eq_u32_e64 s[4:5], v0, v13
	v_mov_b32_e32 v0, 0x2c00
	v_mov_b32_e32 v44, 0xffffd400
	v_mov_b32_e32 v1, v177
	v_mov_b32_e32 v3, v177
	v_lshlrev_b32_e32 v34, 2, v12
	v_lshl_add_u64 v[46:47], v[8:9], 0, v[176:177]
	v_cndmask_b32_e64 v49, -1, 0, vcc
	v_cndmask_b32_e64 v0, v0, 0, s[4:5]
	v_lshl_add_u64 v[42:43], s[6:7], 0, v[6:7]
	v_cndmask_b32_e64 v48, v44, 0, vcc
	global_load_dwordx4 v[6:9], v34, s[18:19] offset:16
	global_load_dwordx4 v[10:13], v34, s[18:19]
	global_load_dwordx4 v[14:17], v34, s[12:13] offset:16
	global_load_dwordx4 v[18:21], v34, s[12:13]
	global_load_dwordx4 v[22:25], v34, s[14:15] offset:16
	global_load_dwordx4 v[26:29], v34, s[14:15]
	global_load_dwordx4 v[30:33], v34, s[30:31] offset:16
	s_nop 0
	global_load_dwordx4 v[34:37], v34, s[30:31]
	v_lshl_add_u64 v[50:51], v[38:39], 0, v[176:177]
	global_load_dwordx4 v[38:41], v[46:47], off
	v_lshl_add_u64 v[0:1], v[46:47], 0, v[0:1]
	v_lshl_add_u64 v[42:43], v[42:43], 0, v[2:3]
	v_lshl_add_u64 v[46:47], v[46:47], 0, v[48:49]
	global_load_dwordx4 v[0:3], v[0:1], off
	s_nop 0
	global_load_dwordx4 v[42:45], v[42:43], off
	v_add_u32_e32 v5, s3, v5
	global_load_dwordx4 v[46:49], v[46:47], off
	s_waitcnt vmcnt(0)
	v_lshlrev_b32_e32 v52, 16, v38
	v_and_b32_e32 v53, 0xffff0000, v38
	v_lshlrev_b32_e32 v54, 16, v40
	v_and_b32_e32 v55, 0xffff0000, v40
	v_lshlrev_b32_e32 v38, 16, v39
	v_and_b32_e32 v39, 0xffff0000, v39
	v_lshlrev_b32_e32 v40, 16, v41
	v_and_b32_e32 v41, 0xffff0000, v41
	v_cndmask_b32_e64 v56, v3, 0, s[4:5]
	v_cndmask_b32_e64 v57, v2, 0, s[4:5]
	v_cndmask_b32_e64 v58, v1, 0, s[4:5]
	v_cndmask_b32_e64 v59, v0, 0, s[4:5]
	v_pk_fma_f32 v[0:1], v[18:19], v[52:53], v[34:35]
	v_pk_mul_f32 v[14:15], v[14:15], v[54:55]
	v_cndmask_b32_e64 v60, v49, 0, vcc
	v_cndmask_b32_e64 v61, v48, 0, vcc
	v_cndmask_b32_e64 v55, v47, 0, vcc
	v_cndmask_b32_e64 v53, v46, 0, vcc
	v_lshlrev_b32_e32 v2, 16, v42
	v_and_b32_e32 v3, 0xffff0000, v42
	v_pk_mul_f32 v[18:19], v[20:21], v[38:39]
	v_lshlrev_b32_e32 v20, 16, v43
	v_and_b32_e32 v21, 0xffff0000, v43
	v_lshlrev_b32_e32 v38, 16, v44
	v_and_b32_e32 v39, 0xffff0000, v44
	v_pk_mul_f32 v[16:17], v[16:17], v[40:41]
	v_lshlrev_b32_e32 v40, 16, v45
	v_and_b32_e32 v41, 0xffff0000, v45
	v_lshlrev_b32_e32 v42, 16, v59
	v_and_b32_e32 v43, 0xffff0000, v59
	v_lshlrev_b32_e32 v44, 16, v58
	v_and_b32_e32 v45, 0xffff0000, v58
	v_lshlrev_b32_e32 v46, 16, v57
	v_and_b32_e32 v47, 0xffff0000, v57
	v_lshlrev_b32_e32 v48, 16, v56
	v_and_b32_e32 v49, 0xffff0000, v56
	v_lshlrev_b32_e32 v52, 16, v53
	v_and_b32_e32 v53, 0xffff0000, v53
	v_lshlrev_b32_e32 v54, 16, v55
	v_and_b32_e32 v55, 0xffff0000, v55
	v_lshlrev_b32_e32 v56, 16, v61
	v_and_b32_e32 v57, 0xffff0000, v61
	v_lshlrev_b32_e32 v58, 16, v60
	v_and_b32_e32 v59, 0xffff0000, v60
	v_pk_fma_f32 v[0:1], v[10:11], v[52:53], v[0:1]
	v_pk_fma_f32 v[10:11], v[12:13], v[54:55], v[18:19]
	v_pk_fma_f32 v[6:7], v[6:7], v[56:57], v[14:15]
	v_pk_fma_f32 v[8:9], v[8:9], v[58:59], v[16:17]
	v_pk_fma_f32 v[0:1], v[26:27], v[42:43], v[0:1]
	v_pk_fma_f32 v[10:11], v[28:29], v[44:45], v[10:11]
	v_pk_fma_f32 v[6:7], v[22:23], v[46:47], v[6:7]
	v_pk_fma_f32 v[8:9], v[24:25], v[48:49], v[8:9]
	v_pk_add_f32 v[10:11], v[36:37], v[10:11]
	v_pk_add_f32 v[6:7], v[30:31], v[6:7]
	v_pk_add_f32 v[8:9], v[32:33], v[8:9]
	v_mul_f32_e32 v12, 0xbfb8aa3b, v0
	v_mul_f32_e32 v13, 0xbfb8aa3b, v1
	v_mul_f32_e32 v14, 0xbfb8aa3b, v10
	v_mul_f32_e32 v15, 0xbfb8aa3b, v11
	v_mul_f32_e32 v16, 0xbfb8aa3b, v6
	v_mul_f32_e32 v17, 0xbfb8aa3b, v7
	v_mul_f32_e32 v18, 0xbfb8aa3b, v8
	v_mul_f32_e32 v19, 0xbfb8aa3b, v9
	v_exp_f32_e32 v12, v12
	v_exp_f32_e32 v13, v13
	v_exp_f32_e32 v14, v14
	v_exp_f32_e32 v15, v15
	v_exp_f32_e32 v16, v16
	v_exp_f32_e32 v17, v17
	v_exp_f32_e32 v18, v18
	v_exp_f32_e32 v19, v19
	v_add_f32_e32 v12, 1.0, v12
	v_add_f32_e32 v13, 1.0, v13
	v_add_f32_e32 v14, 1.0, v14
	v_add_f32_e32 v15, 1.0, v15
	v_add_f32_e32 v16, 1.0, v16
	v_add_f32_e32 v17, 1.0, v17
	v_add_f32_e32 v18, 1.0, v18
	v_add_f32_e32 v19, 1.0, v19
	v_rcp_f32_e32 v12, v12
	v_rcp_f32_e32 v13, v13
	v_rcp_f32_e32 v14, v14
	v_rcp_f32_e32 v15, v15
	v_rcp_f32_e32 v16, v16
	v_rcp_f32_e32 v17, v17
	v_rcp_f32_e32 v18, v18
	v_rcp_f32_e32 v19, v19
	v_pk_mul_f32 v[0:1], v[0:1], v[12:13]
	v_pk_mul_f32 v[10:11], v[10:11], v[14:15]
	v_pk_mul_f32 v[6:7], v[6:7], v[16:17]
	v_pk_mul_f32 v[8:9], v[8:9], v[18:19]
	v_pk_mul_f32 v[0:1], v[0:1], v[2:3]
	v_pk_mul_f32 v[2:3], v[10:11], v[20:21]
	v_pk_mul_f32 v[6:7], v[6:7], v[38:39]
	v_pk_mul_f32 v[8:9], v[8:9], v[40:41]
	v_cvt_pk_bf16_f32 v0, v0, v1
	v_cvt_pk_bf16_f32 v1, v2, v3
	v_cvt_pk_bf16_f32 v2, v6, v7
	v_cvt_pk_bf16_f32 v3, v8, v9
	global_store_dwordx4 v[50:51], v[0:3], off
	s_andn2_b64 exec, exec, s[22:23]
	s_cbranch_execnz .LBB0_1067
